# MFMA snake order: consecutive MFMAs share one operand (src1 pairs kept, src0 alternation reversed every other pair)
# speedup vs baseline: 1.0164x; 1.0164x over previous
.LBB0_139:
	s_add_u32 s22, s18, 0xfff00080
	s_addc_u32 s23, s19, -1
	s_add_i32 s49, 0, 0x10000
	s_cmp_eq_u32 s48, 60
	s_cselect_b32 s25, s9, s23
	s_cselect_b32 s24, s44, s22
	s_cselect_b32 s23, s7, s47
	s_cselect_b32 s22, s45, s46
	s_add_i32 s52, 0, 0x14000
	v_add_u32_e32 v156, s49, v145
	v_add_u32_e32 v172, s52, v145
	ds_read_b128 v[140:143], v156
	ds_read_b128 v[148:151], v156 offset:1024
	ds_read_b128 v[152:155], v156 offset:2048
	ds_read_b128 v[156:159], v156 offset:3072
	ds_read_b128 v[160:163], v172
	ds_read_b128 v[164:167], v172 offset:1024
	ds_read_b128 v[168:171], v172 offset:2048
	ds_read_b128 v[190:193], v172 offset:3072
	v_lshl_add_u64 v[172:173], s[18:19], 0, v[136:137]
	s_add_i32 m0, s31, 0xc000
	ds_read_b128 v[194:197], v147
	ds_read_b128 v[198:201], v147 offset:1024
	ds_read_b128 v[202:205], v147 offset:2048
	ds_read_b128 v[206:209], v147 offset:3072
	ds_read_b128 v[228:231], v147 offset:4096
	ds_read_b128 v[232:235], v147 offset:5120
	ds_read_b128 v[236:239], v147 offset:6144
	ds_read_b128 v[240:243], v147 offset:7168
	global_load_lds_dwordx4 v[172:173], off
	v_lshl_add_u64 v[172:173], s[18:19], 0, v[138:139]
	s_add_i32 m0, s31, 0xe000
	s_nop 0
	global_load_lds_dwordx4 v[172:173], off
	s_waitcnt vmcnt(8)
	s_waitcnt lgkmcnt(0)
	s_barrier
	s_setprio 1
	s_waitcnt lgkmcnt(0)
	v_mfma_f32_16x16x32_bf16 v[126:129], v[140:143], v[194:197], v[126:129]
	v_mfma_f32_16x16x32_bf16 v[122:125], v[152:155], v[194:197], v[122:125]
	v_mfma_f32_16x16x32_bf16 v[110:113], v[152:155], v[202:205], v[110:113]
	v_mfma_f32_16x16x32_bf16 v[118:121], v[140:143], v[202:205], v[118:121]
	v_mfma_f32_16x16x32_bf16 v[102:105], v[140:143], v[228:231], v[102:105]
	v_mfma_f32_16x16x32_bf16 v[94:97], v[152:155], v[228:231], v[94:97]
	v_mfma_f32_16x16x32_bf16 v[78:81], v[152:155], v[236:239], v[78:81]
	v_mfma_f32_16x16x32_bf16 v[86:89], v[140:143], v[236:239], v[86:89]
	v_mfma_f32_16x16x32_bf16 v[126:129], v[148:151], v[198:201], v[126:129]
	v_mfma_f32_16x16x32_bf16 v[122:125], v[156:159], v[198:201], v[122:125]
	v_mfma_f32_16x16x32_bf16 v[110:113], v[156:159], v[206:209], v[110:113]
	v_mfma_f32_16x16x32_bf16 v[118:121], v[148:151], v[206:209], v[118:121]
	v_mfma_f32_16x16x32_bf16 v[102:105], v[148:151], v[232:235], v[102:105]
	v_mfma_f32_16x16x32_bf16 v[94:97], v[156:159], v[232:235], v[94:97]
	v_mfma_f32_16x16x32_bf16 v[78:81], v[156:159], v[240:243], v[78:81]
	v_mfma_f32_16x16x32_bf16 v[86:89], v[148:151], v[240:243], v[86:89]
	s_setprio 0
	s_setprio 1
	v_mfma_f32_16x16x32_bf16 v[114:117], v[160:163], v[194:197], v[114:117]
	v_mfma_f32_16x16x32_bf16 v[106:109], v[168:171], v[194:197], v[106:109]
	v_mfma_f32_16x16x32_bf16 v[90:93], v[168:171], v[202:205], v[90:93]
	v_mfma_f32_16x16x32_bf16 v[98:101], v[160:163], v[202:205], v[98:101]
	v_mfma_f32_16x16x32_bf16 v[82:85], v[160:163], v[228:231], v[82:85]
	v_mfma_f32_16x16x32_bf16 v[74:77], v[168:171], v[228:231], v[74:77]
	v_mfma_f32_16x16x32_bf16 v[66:69], v[168:171], v[236:239], v[66:69]
	v_mfma_f32_16x16x32_bf16 v[70:73], v[160:163], v[236:239], v[70:73]
	v_mfma_f32_16x16x32_bf16 v[114:117], v[164:167], v[198:201], v[114:117]
	v_mfma_f32_16x16x32_bf16 v[106:109], v[190:193], v[198:201], v[106:109]
	v_mfma_f32_16x16x32_bf16 v[90:93], v[190:193], v[206:209], v[90:93]
	v_mfma_f32_16x16x32_bf16 v[98:101], v[164:167], v[206:209], v[98:101]
	v_mfma_f32_16x16x32_bf16 v[82:85], v[164:167], v[232:235], v[82:85]
	v_mfma_f32_16x16x32_bf16 v[74:77], v[190:193], v[232:235], v[74:77]
	v_mfma_f32_16x16x32_bf16 v[66:69], v[190:193], v[240:243], v[66:69]
	v_mfma_f32_16x16x32_bf16 v[70:73], v[164:167], v[240:243], v[70:73]
	s_setprio 0
	s_barrier
	s_add_i32 s49, s49, s26
	v_lshl_add_u64 v[172:173], s[22:23], 0, v[0:1]
	s_mov_b32 m0, s49
	ds_read_b128 v[194:197], v147 offset:16384
	ds_read_b128 v[198:201], v147 offset:17408
	ds_read_b128 v[202:205], v147 offset:18432
	ds_read_b128 v[206:209], v147 offset:19456
	ds_read_b128 v[228:231], v147 offset:20480
	ds_read_b128 v[232:235], v147 offset:21504
	ds_read_b128 v[236:239], v147 offset:22528
	ds_read_b128 v[240:243], v147 offset:23552
	global_load_lds_dwordx4 v[172:173], off
	s_add_i32 m0, s49, 0x2000
	s_add_u32 s50, s22, 0x100000
	v_lshl_add_u64 v[178:179], s[22:23], 0, v[130:131]
	s_addc_u32 s51, s23, 0
	s_add_i32 s49, s52, s26
	global_load_lds_dwordx4 v[178:179], off
	v_lshl_add_u64 v[180:181], s[50:51], 0, v[0:1]
	s_mov_b32 m0, s49
	v_lshl_add_u64 v[210:211], s[24:25], 0, v[132:133]
	global_load_lds_dwordx4 v[180:181], off
	v_lshl_add_u64 v[180:181], s[50:51], 0, v[130:131]
	s_add_i32 m0, s49, 0x2000
	s_nop 0
	global_load_lds_dwordx4 v[180:181], off
	v_lshl_add_u64 v[180:181], s[24:25], 0, v[134:135]
	s_mov_b32 m0, s31
	s_nop 0
	global_load_lds_dwordx4 v[180:181], off
	s_mov_b32 m0, s36
	s_nop 0
	global_load_lds_dwordx4 v[210:211], off
	s_waitcnt vmcnt(8)
	s_waitcnt lgkmcnt(0)
	s_barrier
	s_setprio 1
	s_waitcnt lgkmcnt(0)
	v_mfma_f32_16x16x32_bf16 v[62:65], v[140:143], v[194:197], v[62:65]
	v_mfma_f32_16x16x32_bf16 v[58:61], v[152:155], v[194:197], v[58:61]
	v_mfma_f32_16x16x32_bf16 v[46:49], v[152:155], v[202:205], v[46:49]
	v_mfma_f32_16x16x32_bf16 v[54:57], v[140:143], v[202:205], v[54:57]
	v_mfma_f32_16x16x32_bf16 v[38:41], v[140:143], v[228:231], v[38:41]
	v_mfma_f32_16x16x32_bf16 v[30:33], v[152:155], v[228:231], v[30:33]
	v_mfma_f32_16x16x32_bf16 v[14:17], v[152:155], v[236:239], v[14:17]
	v_mfma_f32_16x16x32_bf16 v[22:25], v[140:143], v[236:239], v[22:25]
	v_mfma_f32_16x16x32_bf16 v[62:65], v[148:151], v[198:201], v[62:65]
	v_mfma_f32_16x16x32_bf16 v[58:61], v[156:159], v[198:201], v[58:61]
	v_mfma_f32_16x16x32_bf16 v[46:49], v[156:159], v[206:209], v[46:49]
	v_mfma_f32_16x16x32_bf16 v[54:57], v[148:151], v[206:209], v[54:57]
	v_mfma_f32_16x16x32_bf16 v[38:41], v[148:151], v[232:235], v[38:41]
	v_mfma_f32_16x16x32_bf16 v[30:33], v[156:159], v[232:235], v[30:33]
	v_mfma_f32_16x16x32_bf16 v[14:17], v[156:159], v[240:243], v[14:17]
	v_mfma_f32_16x16x32_bf16 v[22:25], v[148:151], v[240:243], v[22:25]
	s_setprio 0
	s_setprio 1
	v_mfma_f32_16x16x32_bf16 v[50:53], v[160:163], v[194:197], v[50:53]
	v_mfma_f32_16x16x32_bf16 v[42:45], v[168:171], v[194:197], v[42:45]
	v_mfma_f32_16x16x32_bf16 v[26:29], v[168:171], v[202:205], v[26:29]
	v_mfma_f32_16x16x32_bf16 v[34:37], v[160:163], v[202:205], v[34:37]
	v_mfma_f32_16x16x32_bf16 v[18:21], v[160:163], v[228:231], v[18:21]
	v_mfma_f32_16x16x32_bf16 v[10:13], v[168:171], v[228:231], v[10:13]
	v_mfma_f32_16x16x32_bf16 v[2:5], v[168:171], v[236:239], v[2:5]
	v_mfma_f32_16x16x32_bf16 v[6:9], v[160:163], v[236:239], v[6:9]
	v_mfma_f32_16x16x32_bf16 v[50:53], v[164:167], v[198:201], v[50:53]
	v_mfma_f32_16x16x32_bf16 v[42:45], v[190:193], v[198:201], v[42:45]
	v_mfma_f32_16x16x32_bf16 v[26:29], v[190:193], v[206:209], v[26:29]
	v_mfma_f32_16x16x32_bf16 v[34:37], v[164:167], v[206:209], v[34:37]
	v_mfma_f32_16x16x32_bf16 v[18:21], v[164:167], v[232:235], v[18:21]
	v_mfma_f32_16x16x32_bf16 v[10:13], v[190:193], v[232:235], v[10:13]
	v_mfma_f32_16x16x32_bf16 v[2:5], v[190:193], v[240:243], v[2:5]
	v_mfma_f32_16x16x32_bf16 v[6:9], v[164:167], v[240:243], v[6:9]
	s_setprio 0
	s_barrier
	s_add_i32 s49, 0, 0x18000
	s_add_i32 s50, 0, 0x1c000
	v_add_u32_e32 v156, s49, v145
	v_add_u32_e32 v175, s50, v145
	ds_read_b128 v[140:143], v156
	ds_read_b128 v[148:151], v156 offset:1024
	ds_read_b128 v[152:155], v156 offset:2048
	ds_read_b128 v[156:159], v156 offset:3072
	ds_read_b128 v[160:163], v175
	ds_read_b128 v[164:167], v175 offset:1024
	ds_read_b128 v[168:171], v175 offset:2048
	ds_read_b128 v[190:193], v175 offset:3072
	s_add_u32 s24, s24, 0x100000
	s_addc_u32 s25, s25, 0
	s_mov_b32 m0, s37
	v_lshl_add_u64 v[244:245], s[24:25], 0, v[134:135]
	ds_read_b128 v[194:197], v147 offset:32768
	ds_read_b128 v[198:201], v147 offset:33792
	ds_read_b128 v[202:205], v147 offset:34816
	ds_read_b128 v[206:209], v147 offset:35840
	ds_read_b128 v[228:231], v147 offset:36864
	ds_read_b128 v[232:235], v147 offset:37888
	ds_read_b128 v[236:239], v147 offset:38912
	ds_read_b128 v[240:243], v147 offset:39936
	global_load_lds_dwordx4 v[244:245], off
	v_lshl_add_u64 v[244:245], s[24:25], 0, v[132:133]
	s_mov_b32 m0, s38
	s_nop 0
	global_load_lds_dwordx4 v[244:245], off
	s_waitcnt vmcnt(8)
	s_waitcnt lgkmcnt(0)
	s_barrier
	s_setprio 1
	s_waitcnt lgkmcnt(0)
	v_mfma_f32_16x16x32_bf16 v[126:129], v[140:143], v[194:197], v[126:129]
	v_mfma_f32_16x16x32_bf16 v[122:125], v[152:155], v[194:197], v[122:125]
	v_mfma_f32_16x16x32_bf16 v[110:113], v[152:155], v[202:205], v[110:113]
	v_mfma_f32_16x16x32_bf16 v[118:121], v[140:143], v[202:205], v[118:121]
	v_mfma_f32_16x16x32_bf16 v[102:105], v[140:143], v[228:231], v[102:105]
	v_mfma_f32_16x16x32_bf16 v[94:97], v[152:155], v[228:231], v[94:97]
	v_mfma_f32_16x16x32_bf16 v[78:81], v[152:155], v[236:239], v[78:81]
	v_mfma_f32_16x16x32_bf16 v[86:89], v[140:143], v[236:239], v[86:89]
	v_mfma_f32_16x16x32_bf16 v[126:129], v[148:151], v[198:201], v[126:129]
	v_mfma_f32_16x16x32_bf16 v[122:125], v[156:159], v[198:201], v[122:125]
	v_mfma_f32_16x16x32_bf16 v[110:113], v[156:159], v[206:209], v[110:113]
	v_mfma_f32_16x16x32_bf16 v[118:121], v[148:151], v[206:209], v[118:121]
	v_mfma_f32_16x16x32_bf16 v[102:105], v[148:151], v[232:235], v[102:105]
	v_mfma_f32_16x16x32_bf16 v[94:97], v[156:159], v[232:235], v[94:97]
	v_mfma_f32_16x16x32_bf16 v[78:81], v[156:159], v[240:243], v[78:81]
	v_mfma_f32_16x16x32_bf16 v[86:89], v[148:151], v[240:243], v[86:89]
	s_setprio 0
	s_setprio 1
	v_mfma_f32_16x16x32_bf16 v[114:117], v[160:163], v[194:197], v[114:117]
	v_mfma_f32_16x16x32_bf16 v[106:109], v[168:171], v[194:197], v[106:109]
	v_mfma_f32_16x16x32_bf16 v[90:93], v[168:171], v[202:205], v[90:93]
	v_mfma_f32_16x16x32_bf16 v[98:101], v[160:163], v[202:205], v[98:101]
	v_mfma_f32_16x16x32_bf16 v[82:85], v[160:163], v[228:231], v[82:85]
	v_mfma_f32_16x16x32_bf16 v[74:77], v[168:171], v[228:231], v[74:77]
	v_mfma_f32_16x16x32_bf16 v[66:69], v[168:171], v[236:239], v[66:69]
	v_mfma_f32_16x16x32_bf16 v[70:73], v[160:163], v[236:239], v[70:73]
	v_mfma_f32_16x16x32_bf16 v[114:117], v[164:167], v[198:201], v[114:117]
	v_mfma_f32_16x16x32_bf16 v[106:109], v[190:193], v[198:201], v[106:109]
	v_mfma_f32_16x16x32_bf16 v[90:93], v[190:193], v[206:209], v[90:93]
	v_mfma_f32_16x16x32_bf16 v[98:101], v[164:167], v[206:209], v[98:101]
	v_mfma_f32_16x16x32_bf16 v[82:85], v[164:167], v[232:235], v[82:85]
	v_mfma_f32_16x16x32_bf16 v[74:77], v[190:193], v[232:235], v[74:77]
	v_mfma_f32_16x16x32_bf16 v[66:69], v[190:193], v[240:243], v[66:69]
	v_mfma_f32_16x16x32_bf16 v[70:73], v[164:167], v[240:243], v[70:73]
	s_setprio 0
	s_barrier
	s_add_i32 s24, s49, s26
	v_lshl_add_u64 v[172:173], v[172:173], 0, s[34:35]
	s_mov_b32 m0, s24
	ds_read_b128 v[194:197], v147 offset:49152
	ds_read_b128 v[198:201], v147 offset:50176
	ds_read_b128 v[202:205], v147 offset:51200
	ds_read_b128 v[206:209], v147 offset:52224
	ds_read_b128 v[228:231], v147 offset:53248
	ds_read_b128 v[232:235], v147 offset:54272
	ds_read_b128 v[236:239], v147 offset:55296
	ds_read_b128 v[240:243], v147 offset:56320
	global_load_lds_dwordx4 v[172:173], off
	s_add_i32 m0, s24, 0x2000
	s_add_u32 s22, s22, 0x100080
	v_lshl_add_u64 v[172:173], v[178:179], 0, s[34:35]
	s_addc_u32 s23, s23, 0
	s_add_i32 s24, s50, s26
	global_load_lds_dwordx4 v[172:173], off
	v_lshl_add_u64 v[172:173], s[22:23], 0, v[0:1]
	s_mov_b32 m0, s24
	s_nop 0
	global_load_lds_dwordx4 v[172:173], off
	v_lshl_add_u64 v[172:173], s[22:23], 0, v[130:131]
	s_add_i32 m0, s24, 0x2000
	s_nop 0
	global_load_lds_dwordx4 v[172:173], off
	v_lshl_add_u64 v[172:173], v[180:181], 0, s[34:35]
	s_mov_b32 m0, s39
	s_nop 0
	global_load_lds_dwordx4 v[172:173], off
	v_lshl_add_u64 v[172:173], v[210:211], 0, s[34:35]
	s_mov_b32 m0, s40
	s_nop 0
	global_load_lds_dwordx4 v[172:173], off
	s_waitcnt vmcnt(8)
	s_waitcnt lgkmcnt(0)
	s_barrier
	s_setprio 1
	s_waitcnt lgkmcnt(0)
	v_mfma_f32_16x16x32_bf16 v[62:65], v[140:143], v[194:197], v[62:65]
	v_mfma_f32_16x16x32_bf16 v[58:61], v[152:155], v[194:197], v[58:61]
	v_mfma_f32_16x16x32_bf16 v[46:49], v[152:155], v[202:205], v[46:49]
	v_mfma_f32_16x16x32_bf16 v[54:57], v[140:143], v[202:205], v[54:57]
	v_mfma_f32_16x16x32_bf16 v[38:41], v[140:143], v[228:231], v[38:41]
	v_mfma_f32_16x16x32_bf16 v[30:33], v[152:155], v[228:231], v[30:33]
	v_mfma_f32_16x16x32_bf16 v[14:17], v[152:155], v[236:239], v[14:17]
	v_mfma_f32_16x16x32_bf16 v[22:25], v[140:143], v[236:239], v[22:25]
	v_mfma_f32_16x16x32_bf16 v[62:65], v[148:151], v[198:201], v[62:65]
	v_mfma_f32_16x16x32_bf16 v[58:61], v[156:159], v[198:201], v[58:61]
	v_mfma_f32_16x16x32_bf16 v[46:49], v[156:159], v[206:209], v[46:49]
	v_mfma_f32_16x16x32_bf16 v[54:57], v[148:151], v[206:209], v[54:57]
	v_mfma_f32_16x16x32_bf16 v[38:41], v[148:151], v[232:235], v[38:41]
	v_mfma_f32_16x16x32_bf16 v[30:33], v[156:159], v[232:235], v[30:33]
	v_mfma_f32_16x16x32_bf16 v[14:17], v[156:159], v[240:243], v[14:17]
	v_mfma_f32_16x16x32_bf16 v[22:25], v[148:151], v[240:243], v[22:25]
	s_setprio 0
	s_setprio 1
	v_mfma_f32_16x16x32_bf16 v[50:53], v[160:163], v[194:197], v[50:53]
	v_mfma_f32_16x16x32_bf16 v[42:45], v[168:171], v[194:197], v[42:45]
	v_mfma_f32_16x16x32_bf16 v[26:29], v[168:171], v[202:205], v[26:29]
	v_mfma_f32_16x16x32_bf16 v[34:37], v[160:163], v[202:205], v[34:37]
	v_mfma_f32_16x16x32_bf16 v[18:21], v[160:163], v[228:231], v[18:21]
	v_mfma_f32_16x16x32_bf16 v[10:13], v[168:171], v[228:231], v[10:13]
	v_mfma_f32_16x16x32_bf16 v[2:5], v[168:171], v[236:239], v[2:5]
	v_mfma_f32_16x16x32_bf16 v[6:9], v[160:163], v[236:239], v[6:9]
	v_mfma_f32_16x16x32_bf16 v[50:53], v[164:167], v[198:201], v[50:53]
	v_mfma_f32_16x16x32_bf16 v[42:45], v[190:193], v[198:201], v[42:45]
	v_mfma_f32_16x16x32_bf16 v[26:29], v[190:193], v[206:209], v[26:29]
	v_mfma_f32_16x16x32_bf16 v[34:37], v[164:167], v[206:209], v[34:37]
	v_mfma_f32_16x16x32_bf16 v[18:21], v[164:167], v[232:235], v[18:21]
	v_mfma_f32_16x16x32_bf16 v[10:13], v[190:193], v[232:235], v[10:13]
	v_mfma_f32_16x16x32_bf16 v[2:5], v[190:193], v[240:243], v[2:5]
	v_mfma_f32_16x16x32_bf16 v[6:9], v[164:167], v[240:243], v[6:9]
	s_setprio 0
	s_barrier
	s_add_i32 s48, s48, 2
	s_add_u32 s18, s18, 0x100
	s_addc_u32 s19, s19, 0
	s_add_u32 s46, s46, 0x100
	s_addc_u32 s47, s47, 0
	s_cmp_gt_u32 s48, 61
	s_cbranch_scc0 .LBB0_139
	s_and_b64 vcc, exec, s[4:5]
	s_cbranch_vccz .LBB0_142
	s_barrier

.LBB0_400:
	s_add_u32 s22, s18, 0xfffc0080
	s_addc_u32 s23, s19, -1
	s_add_i32 s54, 0, 0x10000
	s_cmp_eq_u32 s53, 12
	s_cselect_b32 s25, s9, s23
	s_cselect_b32 s24, s49, s22
	s_cselect_b32 s23, s7, s52
	s_cselect_b32 s22, s50, s51
	s_add_i32 s56, 0, 0x14000
	v_add_u32_e32 v54, s54, v177
	v_add_u32_e32 v142, s56, v177
	ds_read_b128 v[34:37], v54
	ds_read_b128 v[38:41], v54 offset:1024
	ds_read_b128 v[50:53], v54 offset:2048
	ds_read_b128 v[54:57], v54 offset:3072
	ds_read_b128 v[106:109], v142
	ds_read_b128 v[118:121], v142 offset:1024
	ds_read_b128 v[130:133], v142 offset:2048
	ds_read_b128 v[142:145], v142 offset:3072
	v_lshl_add_u64 v[186:187], s[18:19], 0, v[196:197]
	s_add_i32 m0, s40, 0xc000
	ds_read_b128 v[146:149], v229
	ds_read_b128 v[158:161], v229 offset:1024
	ds_read_b128 v[162:165], v229 offset:2048
	ds_read_b128 v[178:181], v229 offset:3072
	ds_read_b128 v[200:203], v229 offset:4096
	ds_read_b128 v[204:207], v229 offset:5120
	ds_read_b128 v[208:211], v229 offset:6144
	ds_read_b128 v[230:233], v229 offset:7168
	global_load_lds_dwordx4 v[186:187], off
	v_lshl_add_u64 v[186:187], s[18:19], 0, v[198:199]
	s_add_i32 m0, s40, 0xe000
	s_nop 0
	global_load_lds_dwordx4 v[186:187], off
	s_waitcnt vmcnt(8)
	s_waitcnt lgkmcnt(0)
	s_barrier
	s_setprio 1
	s_waitcnt lgkmcnt(0)
	v_mfma_f32_16x16x32_bf16 v[170:173], v[34:37], v[146:149], v[170:173]
	v_mfma_f32_16x16x32_bf16 v[166:169], v[50:53], v[146:149], v[166:169]
	v_mfma_f32_16x16x32_bf16 v[134:137], v[50:53], v[162:165], v[134:137]
	v_mfma_f32_16x16x32_bf16 v[138:141], v[34:37], v[162:165], v[138:141]
	v_mfma_f32_16x16x32_bf16 v[114:117], v[34:37], v[200:203], v[114:117]
	v_mfma_f32_16x16x32_bf16 v[110:113], v[50:53], v[200:203], v[110:113]
	v_mfma_f32_16x16x32_bf16 v[90:93], v[50:53], v[208:211], v[90:93]
	v_mfma_f32_16x16x32_bf16 v[94:97], v[34:37], v[208:211], v[94:97]
	v_mfma_f32_16x16x32_bf16 v[170:173], v[38:41], v[158:161], v[170:173]
	v_mfma_f32_16x16x32_bf16 v[166:169], v[54:57], v[158:161], v[166:169]
	v_mfma_f32_16x16x32_bf16 v[134:137], v[54:57], v[178:181], v[134:137]
	v_mfma_f32_16x16x32_bf16 v[138:141], v[38:41], v[178:181], v[138:141]
	v_mfma_f32_16x16x32_bf16 v[114:117], v[38:41], v[204:207], v[114:117]
	v_mfma_f32_16x16x32_bf16 v[110:113], v[54:57], v[204:207], v[110:113]
	v_mfma_f32_16x16x32_bf16 v[90:93], v[54:57], v[230:233], v[90:93]
	v_mfma_f32_16x16x32_bf16 v[94:97], v[38:41], v[230:233], v[94:97]
	s_setprio 0
	s_setprio 1
	v_mfma_f32_16x16x32_bf16 v[154:157], v[106:109], v[146:149], v[154:157]
	v_mfma_f32_16x16x32_bf16 v[126:129], v[106:109], v[162:165], v[126:129]
	v_mfma_f32_16x16x32_bf16 v[122:125], v[130:133], v[162:165], v[122:125]
	v_mfma_f32_16x16x32_bf16 v[102:105], v[106:109], v[200:203], v[102:105]
	v_mfma_f32_16x16x32_bf16 v[98:101], v[130:133], v[200:203], v[98:101]
	v_mfma_f32_16x16x32_bf16 v[86:89], v[106:109], v[208:211], v[86:89]
	v_mfma_f32_16x16x32_bf16 v[82:85], v[130:133], v[208:211], v[82:85]
	v_mfma_f32_16x16x32_bf16 v[154:157], v[118:121], v[158:161], v[154:157]
	v_mfma_f32_16x16x32_bf16 v[146:149], v[130:133], v[146:149], v[150:153]
	v_mfma_f32_16x16x32_bf16 v[126:129], v[118:121], v[178:181], v[126:129]
	v_mfma_f32_16x16x32_bf16 v[122:125], v[142:145], v[178:181], v[122:125]
	v_mfma_f32_16x16x32_bf16 v[102:105], v[118:121], v[204:207], v[102:105]
	v_mfma_f32_16x16x32_bf16 v[98:101], v[142:145], v[204:207], v[98:101]
	v_mfma_f32_16x16x32_bf16 v[86:89], v[118:121], v[230:233], v[86:89]
	v_mfma_f32_16x16x32_bf16 v[82:85], v[142:145], v[230:233], v[82:85]
	v_mfma_f32_16x16x32_bf16 v[146:149], v[142:145], v[158:161], v[146:149]
	s_setprio 0
	s_barrier
	s_add_i32 s54, s54, s39
	v_lshl_add_u64 v[186:187], s[22:23], 0, v[0:1]
	s_mov_b32 m0, s54
	ds_read_b128 v[150:153], v229 offset:16384
	ds_read_b128 v[158:161], v229 offset:17408
	ds_read_b128 v[162:165], v229 offset:18432
	ds_read_b128 v[178:181], v229 offset:19456
	ds_read_b128 v[200:203], v229 offset:20480
	ds_read_b128 v[204:207], v229 offset:21504
	ds_read_b128 v[208:211], v229 offset:22528
	ds_read_b128 v[230:233], v229 offset:23552
	global_load_lds_dwordx4 v[186:187], off
	s_add_i32 m0, s54, 0x2000
	s_add_u32 s54, s22, 0x40000
	v_lshl_add_u64 v[188:189], s[22:23], 0, v[190:191]
	s_addc_u32 s55, s23, 0
	s_add_i32 s56, s56, s39
	global_load_lds_dwordx4 v[188:189], off
	v_lshl_add_u64 v[226:227], s[54:55], 0, v[0:1]
	s_mov_b32 m0, s56
	v_lshl_add_u64 v[234:235], s[24:25], 0, v[192:193]
	global_load_lds_dwordx4 v[226:227], off
	v_lshl_add_u64 v[226:227], s[54:55], 0, v[190:191]
	s_add_i32 m0, s56, 0x2000
	s_nop 0
	global_load_lds_dwordx4 v[226:227], off
	v_lshl_add_u64 v[226:227], s[24:25], 0, v[194:195]
	s_mov_b32 m0, s40
	s_nop 0
	global_load_lds_dwordx4 v[226:227], off
	s_mov_b32 m0, s41
	s_nop 0
	global_load_lds_dwordx4 v[234:235], off
	s_waitcnt vmcnt(8)
	s_waitcnt lgkmcnt(0)
	s_barrier
	s_setprio 1
	s_waitcnt lgkmcnt(0)
	v_mfma_f32_16x16x32_bf16 v[78:81], v[34:37], v[150:153], v[78:81]
	v_mfma_f32_16x16x32_bf16 v[74:77], v[50:53], v[150:153], v[74:77]
	v_mfma_f32_16x16x32_bf16 v[58:61], v[50:53], v[162:165], v[58:61]
	v_mfma_f32_16x16x32_bf16 v[62:65], v[34:37], v[162:165], v[62:65]
	v_mfma_f32_16x16x32_bf16 v[30:33], v[34:37], v[200:203], v[30:33]
	v_mfma_f32_16x16x32_bf16 v[26:29], v[50:53], v[200:203], v[26:29]
	v_mfma_f32_16x16x32_bf16 v[10:13], v[50:53], v[208:211], v[10:13]
	v_mfma_f32_16x16x32_bf16 v[14:17], v[34:37], v[208:211], v[14:17]
	v_mfma_f32_16x16x32_bf16 v[78:81], v[38:41], v[158:161], v[78:81]
	v_mfma_f32_16x16x32_bf16 v[74:77], v[54:57], v[158:161], v[74:77]
	v_mfma_f32_16x16x32_bf16 v[58:61], v[54:57], v[178:181], v[58:61]
	v_mfma_f32_16x16x32_bf16 v[62:65], v[38:41], v[178:181], v[62:65]
	v_mfma_f32_16x16x32_bf16 v[30:33], v[38:41], v[204:207], v[30:33]
	v_mfma_f32_16x16x32_bf16 v[26:29], v[54:57], v[204:207], v[26:29]
	v_mfma_f32_16x16x32_bf16 v[10:13], v[54:57], v[230:233], v[10:13]
	v_mfma_f32_16x16x32_bf16 v[14:17], v[38:41], v[230:233], v[14:17]
	s_setprio 0
	s_setprio 1
	v_mfma_f32_16x16x32_bf16 v[46:49], v[106:109], v[162:165], v[46:49]
	v_mfma_f32_16x16x32_bf16 v[42:45], v[130:133], v[162:165], v[42:45]
	v_mfma_f32_16x16x32_bf16 v[18:21], v[130:133], v[200:203], v[18:21]
	v_mfma_f32_16x16x32_bf16 v[22:25], v[106:109], v[200:203], v[22:25]
	v_mfma_f32_16x16x32_bf16 v[6:9], v[106:109], v[208:211], v[6:9]
	v_mfma_f32_16x16x32_bf16 v[2:5], v[130:133], v[208:211], v[2:5]
	v_mfma_f32_16x16x32_bf16 v[38:41], v[130:133], v[150:153], v[66:69]
	v_mfma_f32_16x16x32_bf16 v[34:37], v[106:109], v[150:153], v[70:73]
	v_mfma_f32_16x16x32_bf16 v[46:49], v[118:121], v[178:181], v[46:49]
	v_mfma_f32_16x16x32_bf16 v[42:45], v[142:145], v[178:181], v[42:45]
	v_mfma_f32_16x16x32_bf16 v[18:21], v[142:145], v[204:207], v[18:21]
	v_mfma_f32_16x16x32_bf16 v[22:25], v[118:121], v[204:207], v[22:25]
	v_mfma_f32_16x16x32_bf16 v[6:9], v[118:121], v[230:233], v[6:9]
	v_mfma_f32_16x16x32_bf16 v[2:5], v[142:145], v[230:233], v[2:5]
	v_mfma_f32_16x16x32_bf16 v[38:41], v[142:145], v[158:161], v[38:41]
	v_mfma_f32_16x16x32_bf16 v[34:37], v[118:121], v[158:161], v[34:37]
	s_setprio 0
	s_barrier
	s_add_i32 s54, 0, 0x18000
	s_add_i32 s55, 0, 0x1c000
	v_add_u32_e32 v70, s54, v177
	v_add_u32_e32 v142, s55, v177
	ds_read_b128 v[50:53], v70
	ds_read_b128 v[54:57], v70 offset:1024
	ds_read_b128 v[66:69], v70 offset:2048
	ds_read_b128 v[70:73], v70 offset:3072
	ds_read_b128 v[106:109], v142
	ds_read_b128 v[118:121], v142 offset:1024
	ds_read_b128 v[130:133], v142 offset:2048
	ds_read_b128 v[142:145], v142 offset:3072
	s_add_u32 s24, s24, 0x40000
	s_addc_u32 s25, s25, 0
	s_mov_b32 m0, s42
	v_lshl_add_u64 v[236:237], s[24:25], 0, v[194:195]
	ds_read_b128 v[150:153], v229 offset:32768
	ds_read_b128 v[158:161], v229 offset:33792
	ds_read_b128 v[162:165], v229 offset:34816
	ds_read_b128 v[178:181], v229 offset:35840
	ds_read_b128 v[200:203], v229 offset:36864
	ds_read_b128 v[204:207], v229 offset:37888
	ds_read_b128 v[208:211], v229 offset:38912
	ds_read_b128 v[230:233], v229 offset:39936
	global_load_lds_dwordx4 v[236:237], off
	v_lshl_add_u64 v[236:237], s[24:25], 0, v[192:193]
	s_mov_b32 m0, s43
	s_nop 0
	global_load_lds_dwordx4 v[236:237], off
	s_waitcnt vmcnt(8)
	s_waitcnt lgkmcnt(0)
	s_barrier
	s_setprio 1
	s_waitcnt lgkmcnt(0)
	v_mfma_f32_16x16x32_bf16 v[170:173], v[50:53], v[150:153], v[170:173]
	v_mfma_f32_16x16x32_bf16 v[166:169], v[66:69], v[150:153], v[166:169]
	v_mfma_f32_16x16x32_bf16 v[134:137], v[66:69], v[162:165], v[134:137]
	v_mfma_f32_16x16x32_bf16 v[138:141], v[50:53], v[162:165], v[138:141]
	v_mfma_f32_16x16x32_bf16 v[114:117], v[50:53], v[200:203], v[114:117]
	v_mfma_f32_16x16x32_bf16 v[110:113], v[66:69], v[200:203], v[110:113]
	v_mfma_f32_16x16x32_bf16 v[90:93], v[66:69], v[208:211], v[90:93]
	v_mfma_f32_16x16x32_bf16 v[94:97], v[50:53], v[208:211], v[94:97]
	v_mfma_f32_16x16x32_bf16 v[170:173], v[54:57], v[158:161], v[170:173]
	v_mfma_f32_16x16x32_bf16 v[166:169], v[70:73], v[158:161], v[166:169]
	v_mfma_f32_16x16x32_bf16 v[134:137], v[70:73], v[178:181], v[134:137]
	v_mfma_f32_16x16x32_bf16 v[138:141], v[54:57], v[178:181], v[138:141]
	v_mfma_f32_16x16x32_bf16 v[114:117], v[54:57], v[204:207], v[114:117]
	v_mfma_f32_16x16x32_bf16 v[110:113], v[70:73], v[204:207], v[110:113]
	v_mfma_f32_16x16x32_bf16 v[90:93], v[70:73], v[230:233], v[90:93]
	v_mfma_f32_16x16x32_bf16 v[94:97], v[54:57], v[230:233], v[94:97]
	s_setprio 0
	s_setprio 1
	v_mfma_f32_16x16x32_bf16 v[154:157], v[106:109], v[150:153], v[154:157]
	v_mfma_f32_16x16x32_bf16 v[146:149], v[130:133], v[150:153], v[146:149]
	v_mfma_f32_16x16x32_bf16 v[122:125], v[130:133], v[162:165], v[122:125]
	v_mfma_f32_16x16x32_bf16 v[126:129], v[106:109], v[162:165], v[126:129]
	v_mfma_f32_16x16x32_bf16 v[102:105], v[106:109], v[200:203], v[102:105]
	v_mfma_f32_16x16x32_bf16 v[98:101], v[130:133], v[200:203], v[98:101]
	v_mfma_f32_16x16x32_bf16 v[82:85], v[130:133], v[208:211], v[82:85]
	v_mfma_f32_16x16x32_bf16 v[86:89], v[106:109], v[208:211], v[86:89]
	v_mfma_f32_16x16x32_bf16 v[154:157], v[118:121], v[158:161], v[154:157]
	v_mfma_f32_16x16x32_bf16 v[150:153], v[142:145], v[158:161], v[146:149]
	v_mfma_f32_16x16x32_bf16 v[122:125], v[142:145], v[178:181], v[122:125]
	v_mfma_f32_16x16x32_bf16 v[126:129], v[118:121], v[178:181], v[126:129]
	v_mfma_f32_16x16x32_bf16 v[102:105], v[118:121], v[204:207], v[102:105]
	v_mfma_f32_16x16x32_bf16 v[98:101], v[142:145], v[204:207], v[98:101]
	v_mfma_f32_16x16x32_bf16 v[82:85], v[142:145], v[230:233], v[82:85]
	v_mfma_f32_16x16x32_bf16 v[86:89], v[118:121], v[230:233], v[86:89]
	s_setprio 0
	s_barrier
	s_add_i32 s24, s54, s39
	v_lshl_add_u64 v[186:187], v[186:187], 0, s[34:35]
	s_mov_b32 m0, s24
	ds_read_b128 v[146:149], v229 offset:49152
	ds_read_b128 v[158:161], v229 offset:50176
	ds_read_b128 v[162:165], v229 offset:51200
	ds_read_b128 v[178:181], v229 offset:52224
	ds_read_b128 v[200:203], v229 offset:53248
	ds_read_b128 v[204:207], v229 offset:54272
	ds_read_b128 v[208:211], v229 offset:55296
	ds_read_b128 v[230:233], v229 offset:56320
	global_load_lds_dwordx4 v[186:187], off
	s_add_i32 m0, s24, 0x2000
	s_add_u32 s22, s22, 0x40080
	v_lshl_add_u64 v[186:187], v[188:189], 0, s[34:35]
	s_addc_u32 s23, s23, 0
	s_add_i32 s24, s55, s39
	global_load_lds_dwordx4 v[186:187], off
	v_lshl_add_u64 v[186:187], s[22:23], 0, v[0:1]
	s_mov_b32 m0, s24
	s_nop 0
	global_load_lds_dwordx4 v[186:187], off
	v_lshl_add_u64 v[186:187], s[22:23], 0, v[190:191]
	s_add_i32 m0, s24, 0x2000
	s_nop 0
	global_load_lds_dwordx4 v[186:187], off
	v_lshl_add_u64 v[186:187], v[226:227], 0, s[34:35]
	s_mov_b32 m0, s44
	s_nop 0
	global_load_lds_dwordx4 v[186:187], off
	v_lshl_add_u64 v[186:187], v[234:235], 0, s[34:35]
	s_mov_b32 m0, s45
	s_nop 0
	global_load_lds_dwordx4 v[186:187], off
	s_waitcnt vmcnt(8)
	s_waitcnt lgkmcnt(0)
	s_barrier
	s_setprio 1
	s_waitcnt lgkmcnt(0)
	v_mfma_f32_16x16x32_bf16 v[78:81], v[50:53], v[146:149], v[78:81]
	v_mfma_f32_16x16x32_bf16 v[74:77], v[66:69], v[146:149], v[74:77]
	v_mfma_f32_16x16x32_bf16 v[58:61], v[66:69], v[162:165], v[58:61]
	v_mfma_f32_16x16x32_bf16 v[62:65], v[50:53], v[162:165], v[62:65]
	v_mfma_f32_16x16x32_bf16 v[30:33], v[50:53], v[200:203], v[30:33]
	v_mfma_f32_16x16x32_bf16 v[26:29], v[66:69], v[200:203], v[26:29]
	v_mfma_f32_16x16x32_bf16 v[10:13], v[66:69], v[208:211], v[10:13]
	v_mfma_f32_16x16x32_bf16 v[14:17], v[50:53], v[208:211], v[14:17]
	v_mfma_f32_16x16x32_bf16 v[78:81], v[54:57], v[158:161], v[78:81]
	v_mfma_f32_16x16x32_bf16 v[74:77], v[70:73], v[158:161], v[74:77]
	v_mfma_f32_16x16x32_bf16 v[58:61], v[70:73], v[178:181], v[58:61]
	v_mfma_f32_16x16x32_bf16 v[62:65], v[54:57], v[178:181], v[62:65]
	v_mfma_f32_16x16x32_bf16 v[30:33], v[54:57], v[204:207], v[30:33]
	v_mfma_f32_16x16x32_bf16 v[26:29], v[70:73], v[204:207], v[26:29]
	v_mfma_f32_16x16x32_bf16 v[10:13], v[70:73], v[230:233], v[10:13]
	v_mfma_f32_16x16x32_bf16 v[14:17], v[54:57], v[230:233], v[14:17]
	s_setprio 0
	s_setprio 1
	v_mfma_f32_16x16x32_bf16 v[34:37], v[106:109], v[146:149], v[34:37]
	v_mfma_f32_16x16x32_bf16 v[70:73], v[118:121], v[158:161], v[34:37]
	v_mfma_f32_16x16x32_bf16 v[34:37], v[130:133], v[146:149], v[38:41]
	v_mfma_f32_16x16x32_bf16 v[66:69], v[142:145], v[158:161], v[34:37]
	v_mfma_f32_16x16x32_bf16 v[34:37], v[106:109], v[162:165], v[46:49]
	v_mfma_f32_16x16x32_bf16 v[46:49], v[118:121], v[178:181], v[34:37]
	v_mfma_f32_16x16x32_bf16 v[34:37], v[130:133], v[162:165], v[42:45]
	v_mfma_f32_16x16x32_bf16 v[22:25], v[106:109], v[200:203], v[22:25]
	v_mfma_f32_16x16x32_bf16 v[18:21], v[130:133], v[200:203], v[18:21]
	v_mfma_f32_16x16x32_bf16 v[6:9], v[106:109], v[208:211], v[6:9]
	v_mfma_f32_16x16x32_bf16 v[2:5], v[130:133], v[208:211], v[2:5]
	v_mfma_f32_16x16x32_bf16 v[42:45], v[142:145], v[178:181], v[34:37]
	v_mfma_f32_16x16x32_bf16 v[22:25], v[118:121], v[204:207], v[22:25]
	v_mfma_f32_16x16x32_bf16 v[18:21], v[142:145], v[204:207], v[18:21]
	v_mfma_f32_16x16x32_bf16 v[6:9], v[118:121], v[230:233], v[6:9]
	v_mfma_f32_16x16x32_bf16 v[2:5], v[142:145], v[230:233], v[2:5]
	s_setprio 0
	s_barrier
	s_add_i32 s53, s53, 2
	s_add_u32 s18, s18, 0x100
	s_addc_u32 s19, s19, 0
	s_add_u32 s51, s51, 0x100
	s_addc_u32 s52, s52, 0
	s_cmp_gt_u32 s53, 13
	s_cbranch_scc0 .LBB0_400
	s_and_b64 vcc, exec, s[4:5]
	s_cbranch_vccz .LBB0_403
	s_barrier

.LBB0_575:
	s_add_u32 s22, s18, 0xfff00080
	s_addc_u32 s23, s19, -1
	s_add_i32 s53, 0, 0x10000
	s_cmp_eq_u32 s52, 60
	s_cselect_b32 s25, s9, s23
	s_cselect_b32 s24, s48, s22
	v_add_u32_e32 v140, s53, v143
	s_cselect_b32 s23, s7, s51
	s_cselect_b32 s22, s49, s50
	s_add_i32 s56, 0, 0x14000
	ds_read_b128 v[146:149], v140
	ds_read_b128 v[150:153], v140 offset:1024
	ds_read_b128 v[154:157], v140 offset:2048
	ds_read_b128 v[158:161], v140 offset:3072
	v_add_u32_e32 v140, s56, v143
	ds_read_b128 v[162:165], v140
	ds_read_b128 v[166:169], v140 offset:1024
	ds_read_b128 v[170:173], v140 offset:2048
	ds_read_b128 v[178:181], v140 offset:3072
	v_lshl_add_u64 v[140:141], s[18:19], 0, v[136:137]
	s_add_i32 m0, s39, 0xc000
	ds_read_b128 v[190:193], v145
	ds_read_b128 v[194:197], v145 offset:1024
	ds_read_b128 v[198:201], v145 offset:2048
	ds_read_b128 v[202:205], v145 offset:3072
	ds_read_b128 v[206:209], v145 offset:4096
	ds_read_b128 v[228:231], v145 offset:5120
	ds_read_b128 v[232:235], v145 offset:6144
	ds_read_b128 v[236:239], v145 offset:7168
	global_load_lds_dwordx4 v[140:141], off
	v_lshl_add_u64 v[140:141], s[18:19], 0, v[138:139]
	s_add_i32 m0, s39, 0xe000
	s_nop 0
	global_load_lds_dwordx4 v[140:141], off
	s_waitcnt vmcnt(8)
	s_waitcnt lgkmcnt(0)
	s_barrier
	s_setprio 1
	s_waitcnt lgkmcnt(0)
	v_mfma_f32_16x16x32_bf16 v[126:129], v[146:149], v[190:193], v[126:129]
	v_mfma_f32_16x16x32_bf16 v[122:125], v[154:157], v[190:193], v[122:125]
	v_mfma_f32_16x16x32_bf16 v[110:113], v[154:157], v[198:201], v[110:113]
	v_mfma_f32_16x16x32_bf16 v[118:121], v[146:149], v[198:201], v[118:121]
	v_mfma_f32_16x16x32_bf16 v[102:105], v[146:149], v[206:209], v[102:105]
	v_mfma_f32_16x16x32_bf16 v[94:97], v[154:157], v[206:209], v[94:97]
	v_mfma_f32_16x16x32_bf16 v[78:81], v[154:157], v[232:235], v[78:81]
	v_mfma_f32_16x16x32_bf16 v[86:89], v[146:149], v[232:235], v[86:89]
	v_mfma_f32_16x16x32_bf16 v[126:129], v[150:153], v[194:197], v[126:129]
	v_mfma_f32_16x16x32_bf16 v[122:125], v[158:161], v[194:197], v[122:125]
	v_mfma_f32_16x16x32_bf16 v[110:113], v[158:161], v[202:205], v[110:113]
	v_mfma_f32_16x16x32_bf16 v[118:121], v[150:153], v[202:205], v[118:121]
	v_mfma_f32_16x16x32_bf16 v[102:105], v[150:153], v[228:231], v[102:105]
	v_mfma_f32_16x16x32_bf16 v[94:97], v[158:161], v[228:231], v[94:97]
	v_mfma_f32_16x16x32_bf16 v[78:81], v[158:161], v[236:239], v[78:81]
	v_mfma_f32_16x16x32_bf16 v[86:89], v[150:153], v[236:239], v[86:89]
	s_setprio 0
	s_setprio 1
	v_mfma_f32_16x16x32_bf16 v[114:117], v[162:165], v[190:193], v[114:117]
	v_mfma_f32_16x16x32_bf16 v[106:109], v[170:173], v[190:193], v[106:109]
	v_mfma_f32_16x16x32_bf16 v[90:93], v[170:173], v[198:201], v[90:93]
	v_mfma_f32_16x16x32_bf16 v[98:101], v[162:165], v[198:201], v[98:101]
	v_mfma_f32_16x16x32_bf16 v[82:85], v[162:165], v[206:209], v[82:85]
	v_mfma_f32_16x16x32_bf16 v[74:77], v[170:173], v[206:209], v[74:77]
	v_mfma_f32_16x16x32_bf16 v[66:69], v[170:173], v[232:235], v[66:69]
	v_mfma_f32_16x16x32_bf16 v[70:73], v[162:165], v[232:235], v[70:73]
	v_mfma_f32_16x16x32_bf16 v[114:117], v[166:169], v[194:197], v[114:117]
	v_mfma_f32_16x16x32_bf16 v[106:109], v[178:181], v[194:197], v[106:109]
	v_mfma_f32_16x16x32_bf16 v[90:93], v[178:181], v[202:205], v[90:93]
	v_mfma_f32_16x16x32_bf16 v[98:101], v[166:169], v[202:205], v[98:101]
	v_mfma_f32_16x16x32_bf16 v[82:85], v[166:169], v[228:231], v[82:85]
	v_mfma_f32_16x16x32_bf16 v[74:77], v[178:181], v[228:231], v[74:77]
	v_mfma_f32_16x16x32_bf16 v[66:69], v[178:181], v[236:239], v[66:69]
	v_mfma_f32_16x16x32_bf16 v[70:73], v[166:169], v[236:239], v[70:73]
	s_setprio 0
	s_barrier
	s_add_i32 s53, s53, s38
	v_lshl_add_u64 v[140:141], s[22:23], 0, v[0:1]
	s_mov_b32 m0, s53
	ds_read_b128 v[190:193], v145 offset:16384
	ds_read_b128 v[194:197], v145 offset:17408
	ds_read_b128 v[198:201], v145 offset:18432
	ds_read_b128 v[202:205], v145 offset:19456
	ds_read_b128 v[206:209], v145 offset:20480
	ds_read_b128 v[228:231], v145 offset:21504
	ds_read_b128 v[232:235], v145 offset:22528
	ds_read_b128 v[236:239], v145 offset:23552
	global_load_lds_dwordx4 v[140:141], off
	s_add_i32 m0, s53, 0x2000
	s_add_u32 s54, s22, 0x100000
	v_lshl_add_u64 v[186:187], s[22:23], 0, v[130:131]
	s_addc_u32 s55, s23, 0
	s_add_i32 s53, s56, s38
	global_load_lds_dwordx4 v[186:187], off
	v_lshl_add_u64 v[188:189], s[54:55], 0, v[0:1]
	s_mov_b32 m0, s53
	v_lshl_add_u64 v[210:211], s[24:25], 0, v[132:133]
	global_load_lds_dwordx4 v[188:189], off
	v_lshl_add_u64 v[188:189], s[54:55], 0, v[130:131]
	s_add_i32 m0, s53, 0x2000
	s_nop 0
	global_load_lds_dwordx4 v[188:189], off
	v_lshl_add_u64 v[188:189], s[24:25], 0, v[134:135]
	s_mov_b32 m0, s39
	s_nop 0
	global_load_lds_dwordx4 v[188:189], off
	s_mov_b32 m0, s40
	s_nop 0
	global_load_lds_dwordx4 v[210:211], off
	s_waitcnt vmcnt(8)
	s_waitcnt lgkmcnt(0)
	s_barrier
	s_setprio 1
	s_waitcnt lgkmcnt(0)
	v_mfma_f32_16x16x32_bf16 v[62:65], v[146:149], v[190:193], v[62:65]
	v_mfma_f32_16x16x32_bf16 v[58:61], v[154:157], v[190:193], v[58:61]
	v_mfma_f32_16x16x32_bf16 v[46:49], v[154:157], v[198:201], v[46:49]
	v_mfma_f32_16x16x32_bf16 v[54:57], v[146:149], v[198:201], v[54:57]
	v_mfma_f32_16x16x32_bf16 v[38:41], v[146:149], v[206:209], v[38:41]
	v_mfma_f32_16x16x32_bf16 v[30:33], v[154:157], v[206:209], v[30:33]
	v_mfma_f32_16x16x32_bf16 v[14:17], v[154:157], v[232:235], v[14:17]
	v_mfma_f32_16x16x32_bf16 v[22:25], v[146:149], v[232:235], v[22:25]
	v_mfma_f32_16x16x32_bf16 v[62:65], v[150:153], v[194:197], v[62:65]
	v_mfma_f32_16x16x32_bf16 v[58:61], v[158:161], v[194:197], v[58:61]
	v_mfma_f32_16x16x32_bf16 v[46:49], v[158:161], v[202:205], v[46:49]
	v_mfma_f32_16x16x32_bf16 v[54:57], v[150:153], v[202:205], v[54:57]
	v_mfma_f32_16x16x32_bf16 v[38:41], v[150:153], v[228:231], v[38:41]
	v_mfma_f32_16x16x32_bf16 v[30:33], v[158:161], v[228:231], v[30:33]
	v_mfma_f32_16x16x32_bf16 v[14:17], v[158:161], v[236:239], v[14:17]
	v_mfma_f32_16x16x32_bf16 v[22:25], v[150:153], v[236:239], v[22:25]
	s_setprio 0
	s_setprio 1
	v_mfma_f32_16x16x32_bf16 v[50:53], v[162:165], v[190:193], v[50:53]
	v_mfma_f32_16x16x32_bf16 v[42:45], v[170:173], v[190:193], v[42:45]
	v_mfma_f32_16x16x32_bf16 v[26:29], v[170:173], v[198:201], v[26:29]
	v_mfma_f32_16x16x32_bf16 v[34:37], v[162:165], v[198:201], v[34:37]
	v_mfma_f32_16x16x32_bf16 v[18:21], v[162:165], v[206:209], v[18:21]
	v_mfma_f32_16x16x32_bf16 v[10:13], v[170:173], v[206:209], v[10:13]
	v_mfma_f32_16x16x32_bf16 v[2:5], v[170:173], v[232:235], v[2:5]
	v_mfma_f32_16x16x32_bf16 v[6:9], v[162:165], v[232:235], v[6:9]
	v_mfma_f32_16x16x32_bf16 v[50:53], v[166:169], v[194:197], v[50:53]
	v_mfma_f32_16x16x32_bf16 v[42:45], v[178:181], v[194:197], v[42:45]
	v_mfma_f32_16x16x32_bf16 v[26:29], v[178:181], v[202:205], v[26:29]
	v_mfma_f32_16x16x32_bf16 v[34:37], v[166:169], v[202:205], v[34:37]
	v_mfma_f32_16x16x32_bf16 v[18:21], v[166:169], v[228:231], v[18:21]
	v_mfma_f32_16x16x32_bf16 v[10:13], v[178:181], v[228:231], v[10:13]
	v_mfma_f32_16x16x32_bf16 v[2:5], v[178:181], v[236:239], v[2:5]
	v_mfma_f32_16x16x32_bf16 v[6:9], v[166:169], v[236:239], v[6:9]
	s_setprio 0
	s_barrier
	s_add_i32 s53, 0, 0x18000
	s_add_i32 s54, 0, 0x1c000
	v_add_u32_e32 v158, s53, v143
	v_add_u32_e32 v175, s54, v143
	ds_read_b128 v[146:149], v158
	ds_read_b128 v[150:153], v158 offset:1024
	ds_read_b128 v[154:157], v158 offset:2048
	ds_read_b128 v[158:161], v158 offset:3072
	ds_read_b128 v[162:165], v175
	ds_read_b128 v[166:169], v175 offset:1024
	ds_read_b128 v[170:173], v175 offset:2048
	ds_read_b128 v[178:181], v175 offset:3072
	s_add_u32 s24, s24, 0x100000
	s_addc_u32 s25, s25, 0
	s_mov_b32 m0, s41
	v_lshl_add_u64 v[226:227], s[24:25], 0, v[134:135]
	ds_read_b128 v[190:193], v145 offset:32768
	ds_read_b128 v[194:197], v145 offset:33792
	ds_read_b128 v[198:201], v145 offset:34816
	ds_read_b128 v[202:205], v145 offset:35840
	ds_read_b128 v[206:209], v145 offset:36864
	ds_read_b128 v[228:231], v145 offset:37888
	ds_read_b128 v[232:235], v145 offset:38912
	ds_read_b128 v[236:239], v145 offset:39936
	global_load_lds_dwordx4 v[226:227], off
	v_lshl_add_u64 v[226:227], s[24:25], 0, v[132:133]
	s_mov_b32 m0, s42
	s_nop 0
	global_load_lds_dwordx4 v[226:227], off
	s_waitcnt vmcnt(8)
	s_waitcnt lgkmcnt(0)
	s_barrier
	s_setprio 1
	s_waitcnt lgkmcnt(0)
	v_mfma_f32_16x16x32_bf16 v[126:129], v[146:149], v[190:193], v[126:129]
	v_mfma_f32_16x16x32_bf16 v[122:125], v[154:157], v[190:193], v[122:125]
	v_mfma_f32_16x16x32_bf16 v[110:113], v[154:157], v[198:201], v[110:113]
	v_mfma_f32_16x16x32_bf16 v[118:121], v[146:149], v[198:201], v[118:121]
	v_mfma_f32_16x16x32_bf16 v[102:105], v[146:149], v[206:209], v[102:105]
	v_mfma_f32_16x16x32_bf16 v[94:97], v[154:157], v[206:209], v[94:97]
	v_mfma_f32_16x16x32_bf16 v[78:81], v[154:157], v[232:235], v[78:81]
	v_mfma_f32_16x16x32_bf16 v[86:89], v[146:149], v[232:235], v[86:89]
	v_mfma_f32_16x16x32_bf16 v[126:129], v[150:153], v[194:197], v[126:129]
	v_mfma_f32_16x16x32_bf16 v[122:125], v[158:161], v[194:197], v[122:125]
	v_mfma_f32_16x16x32_bf16 v[110:113], v[158:161], v[202:205], v[110:113]
	v_mfma_f32_16x16x32_bf16 v[118:121], v[150:153], v[202:205], v[118:121]
	v_mfma_f32_16x16x32_bf16 v[102:105], v[150:153], v[228:231], v[102:105]
	v_mfma_f32_16x16x32_bf16 v[94:97], v[158:161], v[228:231], v[94:97]
	v_mfma_f32_16x16x32_bf16 v[78:81], v[158:161], v[236:239], v[78:81]
	v_mfma_f32_16x16x32_bf16 v[86:89], v[150:153], v[236:239], v[86:89]
	s_setprio 0
	s_setprio 1
	v_mfma_f32_16x16x32_bf16 v[114:117], v[162:165], v[190:193], v[114:117]
	v_mfma_f32_16x16x32_bf16 v[106:109], v[170:173], v[190:193], v[106:109]
	v_mfma_f32_16x16x32_bf16 v[90:93], v[170:173], v[198:201], v[90:93]
	v_mfma_f32_16x16x32_bf16 v[98:101], v[162:165], v[198:201], v[98:101]
	v_mfma_f32_16x16x32_bf16 v[82:85], v[162:165], v[206:209], v[82:85]
	v_mfma_f32_16x16x32_bf16 v[74:77], v[170:173], v[206:209], v[74:77]
	v_mfma_f32_16x16x32_bf16 v[66:69], v[170:173], v[232:235], v[66:69]
	v_mfma_f32_16x16x32_bf16 v[70:73], v[162:165], v[232:235], v[70:73]
	v_mfma_f32_16x16x32_bf16 v[114:117], v[166:169], v[194:197], v[114:117]
	v_mfma_f32_16x16x32_bf16 v[106:109], v[178:181], v[194:197], v[106:109]
	v_mfma_f32_16x16x32_bf16 v[90:93], v[178:181], v[202:205], v[90:93]
	v_mfma_f32_16x16x32_bf16 v[98:101], v[166:169], v[202:205], v[98:101]
	v_mfma_f32_16x16x32_bf16 v[82:85], v[166:169], v[228:231], v[82:85]
	v_mfma_f32_16x16x32_bf16 v[74:77], v[178:181], v[228:231], v[74:77]
	v_mfma_f32_16x16x32_bf16 v[66:69], v[178:181], v[236:239], v[66:69]
	v_mfma_f32_16x16x32_bf16 v[70:73], v[166:169], v[236:239], v[70:73]
	s_setprio 0
	s_barrier
	s_add_i32 s24, s53, s38
	v_lshl_add_u64 v[140:141], v[140:141], 0, s[34:35]
	s_mov_b32 m0, s24
	ds_read_b128 v[190:193], v145 offset:49152
	ds_read_b128 v[194:197], v145 offset:50176
	ds_read_b128 v[198:201], v145 offset:51200
	ds_read_b128 v[202:205], v145 offset:52224
	ds_read_b128 v[206:209], v145 offset:53248
	ds_read_b128 v[228:231], v145 offset:54272
	ds_read_b128 v[232:235], v145 offset:55296
	ds_read_b128 v[236:239], v145 offset:56320
	global_load_lds_dwordx4 v[140:141], off
	s_add_i32 m0, s24, 0x2000
	s_add_u32 s22, s22, 0x100080
	v_lshl_add_u64 v[140:141], v[186:187], 0, s[34:35]
	s_addc_u32 s23, s23, 0
	s_add_i32 s24, s54, s38
	global_load_lds_dwordx4 v[140:141], off
	v_lshl_add_u64 v[140:141], s[22:23], 0, v[0:1]
	s_mov_b32 m0, s24
	s_nop 0
	global_load_lds_dwordx4 v[140:141], off
	v_lshl_add_u64 v[140:141], s[22:23], 0, v[130:131]
	s_add_i32 m0, s24, 0x2000
	s_nop 0
	global_load_lds_dwordx4 v[140:141], off
	v_lshl_add_u64 v[140:141], v[188:189], 0, s[34:35]
	s_mov_b32 m0, s43
	s_nop 0
	global_load_lds_dwordx4 v[140:141], off
	v_lshl_add_u64 v[140:141], v[210:211], 0, s[34:35]
	s_mov_b32 m0, s44
	s_nop 0
	global_load_lds_dwordx4 v[140:141], off
	s_waitcnt vmcnt(8)
	s_waitcnt lgkmcnt(0)
	s_barrier
	s_setprio 1
	s_waitcnt lgkmcnt(0)
	v_mfma_f32_16x16x32_bf16 v[62:65], v[146:149], v[190:193], v[62:65]
	v_mfma_f32_16x16x32_bf16 v[58:61], v[154:157], v[190:193], v[58:61]
	v_mfma_f32_16x16x32_bf16 v[46:49], v[154:157], v[198:201], v[46:49]
	v_mfma_f32_16x16x32_bf16 v[54:57], v[146:149], v[198:201], v[54:57]
	v_mfma_f32_16x16x32_bf16 v[38:41], v[146:149], v[206:209], v[38:41]
	v_mfma_f32_16x16x32_bf16 v[30:33], v[154:157], v[206:209], v[30:33]
	v_mfma_f32_16x16x32_bf16 v[14:17], v[154:157], v[232:235], v[14:17]
	v_mfma_f32_16x16x32_bf16 v[22:25], v[146:149], v[232:235], v[22:25]
	v_mfma_f32_16x16x32_bf16 v[62:65], v[150:153], v[194:197], v[62:65]
	v_mfma_f32_16x16x32_bf16 v[58:61], v[158:161], v[194:197], v[58:61]
	v_mfma_f32_16x16x32_bf16 v[46:49], v[158:161], v[202:205], v[46:49]
	v_mfma_f32_16x16x32_bf16 v[54:57], v[150:153], v[202:205], v[54:57]
	v_mfma_f32_16x16x32_bf16 v[38:41], v[150:153], v[228:231], v[38:41]
	v_mfma_f32_16x16x32_bf16 v[30:33], v[158:161], v[228:231], v[30:33]
	v_mfma_f32_16x16x32_bf16 v[14:17], v[158:161], v[236:239], v[14:17]
	v_mfma_f32_16x16x32_bf16 v[22:25], v[150:153], v[236:239], v[22:25]
	s_setprio 0
	s_setprio 1
	v_mfma_f32_16x16x32_bf16 v[50:53], v[162:165], v[190:193], v[50:53]
	v_mfma_f32_16x16x32_bf16 v[42:45], v[170:173], v[190:193], v[42:45]
	v_mfma_f32_16x16x32_bf16 v[26:29], v[170:173], v[198:201], v[26:29]
	v_mfma_f32_16x16x32_bf16 v[34:37], v[162:165], v[198:201], v[34:37]
	v_mfma_f32_16x16x32_bf16 v[18:21], v[162:165], v[206:209], v[18:21]
	v_mfma_f32_16x16x32_bf16 v[10:13], v[170:173], v[206:209], v[10:13]
	v_mfma_f32_16x16x32_bf16 v[2:5], v[170:173], v[232:235], v[2:5]
	v_mfma_f32_16x16x32_bf16 v[6:9], v[162:165], v[232:235], v[6:9]
	v_mfma_f32_16x16x32_bf16 v[50:53], v[166:169], v[194:197], v[50:53]
	v_mfma_f32_16x16x32_bf16 v[42:45], v[178:181], v[194:197], v[42:45]
	v_mfma_f32_16x16x32_bf16 v[26:29], v[178:181], v[202:205], v[26:29]
	v_mfma_f32_16x16x32_bf16 v[34:37], v[166:169], v[202:205], v[34:37]
	v_mfma_f32_16x16x32_bf16 v[18:21], v[166:169], v[228:231], v[18:21]
	v_mfma_f32_16x16x32_bf16 v[10:13], v[178:181], v[228:231], v[10:13]
	v_mfma_f32_16x16x32_bf16 v[2:5], v[178:181], v[236:239], v[2:5]
	v_mfma_f32_16x16x32_bf16 v[6:9], v[166:169], v[236:239], v[6:9]
	s_setprio 0
	s_barrier
	s_add_i32 s52, s52, 2
	s_add_u32 s18, s18, 0x100
	s_addc_u32 s19, s19, 0
	s_add_u32 s50, s50, 0x100
	s_addc_u32 s51, s51, 0
	s_cmp_gt_u32 s52, 61
	s_cbranch_scc0 .LBB0_575
	s_and_b64 vcc, exec, s[4:5]
	s_cbranch_vccz .LBB0_578
	s_barrier

.LBB0_721:
	s_add_u32 s18, s16, 0xfff00080
	s_addc_u32 s19, s17, -1
	s_add_i32 s53, 0, 0x10000
	s_cmp_eq_u32 s52, 60
	s_cselect_b32 s23, s7, s19
	s_cselect_b32 s22, s48, s18
	v_add_u32_e32 v140, s53, v143
	s_cselect_b32 s19, s5, s51
	s_cselect_b32 s18, s49, s50
	s_add_i32 s56, 0, 0x14000
	ds_read_b128 v[146:149], v140
	ds_read_b128 v[150:153], v140 offset:1024
	ds_read_b128 v[154:157], v140 offset:2048
	ds_read_b128 v[158:161], v140 offset:3072
	v_add_u32_e32 v140, s56, v143
	ds_read_b128 v[162:165], v140
	ds_read_b128 v[166:169], v140 offset:1024
	ds_read_b128 v[170:173], v140 offset:2048
	ds_read_b128 v[178:181], v140 offset:3072
	v_lshl_add_u64 v[140:141], s[16:17], 0, v[136:137]
	s_add_i32 m0, s31, 0xc000
	ds_read_b128 v[190:193], v145
	ds_read_b128 v[194:197], v145 offset:1024
	ds_read_b128 v[198:201], v145 offset:2048
	ds_read_b128 v[202:205], v145 offset:3072
	ds_read_b128 v[206:209], v145 offset:4096
	ds_read_b128 v[228:231], v145 offset:5120
	ds_read_b128 v[232:235], v145 offset:6144
	ds_read_b128 v[236:239], v145 offset:7168
	global_load_lds_dwordx4 v[140:141], off
	v_lshl_add_u64 v[140:141], s[16:17], 0, v[138:139]
	s_add_i32 m0, s31, 0xe000
	s_nop 0
	global_load_lds_dwordx4 v[140:141], off
	s_waitcnt vmcnt(8)
	s_waitcnt lgkmcnt(0)
	s_barrier
	s_setprio 1
	s_waitcnt lgkmcnt(0)
	v_mfma_f32_16x16x32_bf16 v[126:129], v[146:149], v[190:193], v[126:129]
	v_mfma_f32_16x16x32_bf16 v[118:121], v[154:157], v[190:193], v[118:121]
	v_mfma_f32_16x16x32_bf16 v[102:105], v[154:157], v[198:201], v[102:105]
	v_mfma_f32_16x16x32_bf16 v[110:113], v[146:149], v[198:201], v[110:113]
	v_mfma_f32_16x16x32_bf16 v[94:97], v[146:149], v[206:209], v[94:97]
	v_mfma_f32_16x16x32_bf16 v[86:89], v[154:157], v[206:209], v[86:89]
	v_mfma_f32_16x16x32_bf16 v[70:73], v[154:157], v[232:235], v[70:73]
	v_mfma_f32_16x16x32_bf16 v[78:81], v[146:149], v[232:235], v[78:81]
	v_mfma_f32_16x16x32_bf16 v[126:129], v[150:153], v[194:197], v[126:129]
	v_mfma_f32_16x16x32_bf16 v[118:121], v[158:161], v[194:197], v[118:121]
	v_mfma_f32_16x16x32_bf16 v[102:105], v[158:161], v[202:205], v[102:105]
	v_mfma_f32_16x16x32_bf16 v[110:113], v[150:153], v[202:205], v[110:113]
	v_mfma_f32_16x16x32_bf16 v[94:97], v[150:153], v[228:231], v[94:97]
	v_mfma_f32_16x16x32_bf16 v[86:89], v[158:161], v[228:231], v[86:89]
	v_mfma_f32_16x16x32_bf16 v[70:73], v[158:161], v[236:239], v[70:73]
	v_mfma_f32_16x16x32_bf16 v[78:81], v[150:153], v[236:239], v[78:81]
	s_setprio 0
	s_setprio 1
	v_mfma_f32_16x16x32_bf16 v[122:125], v[162:165], v[190:193], v[122:125]
	v_mfma_f32_16x16x32_bf16 v[114:117], v[170:173], v[190:193], v[114:117]
	v_mfma_f32_16x16x32_bf16 v[98:101], v[170:173], v[198:201], v[98:101]
	v_mfma_f32_16x16x32_bf16 v[106:109], v[162:165], v[198:201], v[106:109]
	v_mfma_f32_16x16x32_bf16 v[90:93], v[162:165], v[206:209], v[90:93]
	v_mfma_f32_16x16x32_bf16 v[82:85], v[170:173], v[206:209], v[82:85]
	v_mfma_f32_16x16x32_bf16 v[66:69], v[170:173], v[232:235], v[66:69]
	v_mfma_f32_16x16x32_bf16 v[74:77], v[162:165], v[232:235], v[74:77]
	v_mfma_f32_16x16x32_bf16 v[122:125], v[166:169], v[194:197], v[122:125]
	v_mfma_f32_16x16x32_bf16 v[114:117], v[178:181], v[194:197], v[114:117]
	v_mfma_f32_16x16x32_bf16 v[98:101], v[178:181], v[202:205], v[98:101]
	v_mfma_f32_16x16x32_bf16 v[106:109], v[166:169], v[202:205], v[106:109]
	v_mfma_f32_16x16x32_bf16 v[90:93], v[166:169], v[228:231], v[90:93]
	v_mfma_f32_16x16x32_bf16 v[82:85], v[178:181], v[228:231], v[82:85]
	v_mfma_f32_16x16x32_bf16 v[66:69], v[178:181], v[236:239], v[66:69]
	v_mfma_f32_16x16x32_bf16 v[74:77], v[166:169], v[236:239], v[74:77]
	s_setprio 0
	s_barrier
	s_add_i32 s53, s53, s26
	v_lshl_add_u64 v[140:141], s[18:19], 0, v[0:1]
	s_mov_b32 m0, s53
	ds_read_b128 v[190:193], v145 offset:16384
	ds_read_b128 v[194:197], v145 offset:17408
	ds_read_b128 v[198:201], v145 offset:18432
	ds_read_b128 v[202:205], v145 offset:19456
	ds_read_b128 v[206:209], v145 offset:20480
	ds_read_b128 v[228:231], v145 offset:21504
	ds_read_b128 v[232:235], v145 offset:22528
	ds_read_b128 v[236:239], v145 offset:23552
	global_load_lds_dwordx4 v[140:141], off
	s_add_i32 m0, s53, 0x2000
	s_add_u32 s54, s18, 0x100000
	v_lshl_add_u64 v[186:187], s[18:19], 0, v[130:131]
	s_addc_u32 s55, s19, 0
	s_add_i32 s53, s56, s26
	global_load_lds_dwordx4 v[186:187], off
	v_lshl_add_u64 v[188:189], s[54:55], 0, v[0:1]
	s_mov_b32 m0, s53
	v_lshl_add_u64 v[210:211], s[22:23], 0, v[132:133]
	global_load_lds_dwordx4 v[188:189], off
	v_lshl_add_u64 v[188:189], s[54:55], 0, v[130:131]
	s_add_i32 m0, s53, 0x2000
	s_nop 0
	global_load_lds_dwordx4 v[188:189], off
	v_lshl_add_u64 v[188:189], s[22:23], 0, v[134:135]
	s_mov_b32 m0, s31
	s_nop 0
	global_load_lds_dwordx4 v[188:189], off
	s_mov_b32 m0, s40
	s_nop 0
	global_load_lds_dwordx4 v[210:211], off
	s_waitcnt vmcnt(8)
	s_waitcnt lgkmcnt(0)
	s_barrier
	s_setprio 1
	s_waitcnt lgkmcnt(0)
	v_mfma_f32_16x16x32_bf16 v[62:65], v[146:149], v[190:193], v[62:65]
	v_mfma_f32_16x16x32_bf16 v[54:57], v[154:157], v[190:193], v[54:57]
	v_mfma_f32_16x16x32_bf16 v[38:41], v[154:157], v[198:201], v[38:41]
	v_mfma_f32_16x16x32_bf16 v[46:49], v[146:149], v[198:201], v[46:49]
	v_mfma_f32_16x16x32_bf16 v[30:33], v[146:149], v[206:209], v[30:33]
	v_mfma_f32_16x16x32_bf16 v[22:25], v[154:157], v[206:209], v[22:25]
	v_mfma_f32_16x16x32_bf16 v[6:9], v[154:157], v[232:235], v[6:9]
	v_mfma_f32_16x16x32_bf16 v[14:17], v[146:149], v[232:235], v[14:17]
	v_mfma_f32_16x16x32_bf16 v[62:65], v[150:153], v[194:197], v[62:65]
	v_mfma_f32_16x16x32_bf16 v[54:57], v[158:161], v[194:197], v[54:57]
	v_mfma_f32_16x16x32_bf16 v[38:41], v[158:161], v[202:205], v[38:41]
	v_mfma_f32_16x16x32_bf16 v[46:49], v[150:153], v[202:205], v[46:49]
	v_mfma_f32_16x16x32_bf16 v[30:33], v[150:153], v[228:231], v[30:33]
	v_mfma_f32_16x16x32_bf16 v[22:25], v[158:161], v[228:231], v[22:25]
	v_mfma_f32_16x16x32_bf16 v[6:9], v[158:161], v[236:239], v[6:9]
	v_mfma_f32_16x16x32_bf16 v[14:17], v[150:153], v[236:239], v[14:17]
	s_setprio 0
	s_setprio 1
	v_mfma_f32_16x16x32_bf16 v[58:61], v[162:165], v[190:193], v[58:61]
	v_mfma_f32_16x16x32_bf16 v[50:53], v[170:173], v[190:193], v[50:53]
	v_mfma_f32_16x16x32_bf16 v[34:37], v[170:173], v[198:201], v[34:37]
	v_mfma_f32_16x16x32_bf16 v[42:45], v[162:165], v[198:201], v[42:45]
	v_mfma_f32_16x16x32_bf16 v[26:29], v[162:165], v[206:209], v[26:29]
	v_mfma_f32_16x16x32_bf16 v[18:21], v[170:173], v[206:209], v[18:21]
	v_mfma_f32_16x16x32_bf16 v[2:5], v[170:173], v[232:235], v[2:5]
	v_mfma_f32_16x16x32_bf16 v[10:13], v[162:165], v[232:235], v[10:13]
	v_mfma_f32_16x16x32_bf16 v[58:61], v[166:169], v[194:197], v[58:61]
	v_mfma_f32_16x16x32_bf16 v[50:53], v[178:181], v[194:197], v[50:53]
	v_mfma_f32_16x16x32_bf16 v[34:37], v[178:181], v[202:205], v[34:37]
	v_mfma_f32_16x16x32_bf16 v[42:45], v[166:169], v[202:205], v[42:45]
	v_mfma_f32_16x16x32_bf16 v[26:29], v[166:169], v[228:231], v[26:29]
	v_mfma_f32_16x16x32_bf16 v[18:21], v[178:181], v[228:231], v[18:21]
	v_mfma_f32_16x16x32_bf16 v[2:5], v[178:181], v[236:239], v[2:5]
	v_mfma_f32_16x16x32_bf16 v[10:13], v[166:169], v[236:239], v[10:13]
	s_setprio 0
	s_barrier
	s_add_i32 s53, 0, 0x18000
	s_add_i32 s54, 0, 0x1c000
	v_add_u32_e32 v158, s53, v143
	v_add_u32_e32 v175, s54, v143
	ds_read_b128 v[146:149], v158
	ds_read_b128 v[150:153], v158 offset:1024
	ds_read_b128 v[154:157], v158 offset:2048
	ds_read_b128 v[158:161], v158 offset:3072
	ds_read_b128 v[162:165], v175
	ds_read_b128 v[166:169], v175 offset:1024
	ds_read_b128 v[170:173], v175 offset:2048
	ds_read_b128 v[178:181], v175 offset:3072
	s_add_u32 s22, s22, 0x100000
	s_addc_u32 s23, s23, 0
	s_mov_b32 m0, s41
	v_lshl_add_u64 v[226:227], s[22:23], 0, v[134:135]
	ds_read_b128 v[190:193], v145 offset:32768
	ds_read_b128 v[194:197], v145 offset:33792
	ds_read_b128 v[198:201], v145 offset:34816
	ds_read_b128 v[202:205], v145 offset:35840
	ds_read_b128 v[206:209], v145 offset:36864
	ds_read_b128 v[228:231], v145 offset:37888
	ds_read_b128 v[232:235], v145 offset:38912
	ds_read_b128 v[236:239], v145 offset:39936
	global_load_lds_dwordx4 v[226:227], off
	v_lshl_add_u64 v[226:227], s[22:23], 0, v[132:133]
	s_mov_b32 m0, s42
	s_nop 0
	global_load_lds_dwordx4 v[226:227], off
	s_waitcnt vmcnt(8)
	s_waitcnt lgkmcnt(0)
	s_barrier
	s_setprio 1
	s_waitcnt lgkmcnt(0)
	v_mfma_f32_16x16x32_bf16 v[126:129], v[146:149], v[190:193], v[126:129]
	v_mfma_f32_16x16x32_bf16 v[118:121], v[154:157], v[190:193], v[118:121]
	v_mfma_f32_16x16x32_bf16 v[102:105], v[154:157], v[198:201], v[102:105]
	v_mfma_f32_16x16x32_bf16 v[110:113], v[146:149], v[198:201], v[110:113]
	v_mfma_f32_16x16x32_bf16 v[94:97], v[146:149], v[206:209], v[94:97]
	v_mfma_f32_16x16x32_bf16 v[86:89], v[154:157], v[206:209], v[86:89]
	v_mfma_f32_16x16x32_bf16 v[70:73], v[154:157], v[232:235], v[70:73]
	v_mfma_f32_16x16x32_bf16 v[78:81], v[146:149], v[232:235], v[78:81]
	v_mfma_f32_16x16x32_bf16 v[126:129], v[150:153], v[194:197], v[126:129]
	v_mfma_f32_16x16x32_bf16 v[118:121], v[158:161], v[194:197], v[118:121]
	v_mfma_f32_16x16x32_bf16 v[102:105], v[158:161], v[202:205], v[102:105]
	v_mfma_f32_16x16x32_bf16 v[110:113], v[150:153], v[202:205], v[110:113]
	v_mfma_f32_16x16x32_bf16 v[94:97], v[150:153], v[228:231], v[94:97]
	v_mfma_f32_16x16x32_bf16 v[86:89], v[158:161], v[228:231], v[86:89]
	v_mfma_f32_16x16x32_bf16 v[70:73], v[158:161], v[236:239], v[70:73]
	v_mfma_f32_16x16x32_bf16 v[78:81], v[150:153], v[236:239], v[78:81]
	s_setprio 0
	s_setprio 1
	v_mfma_f32_16x16x32_bf16 v[122:125], v[162:165], v[190:193], v[122:125]
	v_mfma_f32_16x16x32_bf16 v[114:117], v[170:173], v[190:193], v[114:117]
	v_mfma_f32_16x16x32_bf16 v[98:101], v[170:173], v[198:201], v[98:101]
	v_mfma_f32_16x16x32_bf16 v[106:109], v[162:165], v[198:201], v[106:109]
	v_mfma_f32_16x16x32_bf16 v[90:93], v[162:165], v[206:209], v[90:93]
	v_mfma_f32_16x16x32_bf16 v[82:85], v[170:173], v[206:209], v[82:85]
	v_mfma_f32_16x16x32_bf16 v[66:69], v[170:173], v[232:235], v[66:69]
	v_mfma_f32_16x16x32_bf16 v[74:77], v[162:165], v[232:235], v[74:77]
	v_mfma_f32_16x16x32_bf16 v[122:125], v[166:169], v[194:197], v[122:125]
	v_mfma_f32_16x16x32_bf16 v[114:117], v[178:181], v[194:197], v[114:117]
	v_mfma_f32_16x16x32_bf16 v[98:101], v[178:181], v[202:205], v[98:101]
	v_mfma_f32_16x16x32_bf16 v[106:109], v[166:169], v[202:205], v[106:109]
	v_mfma_f32_16x16x32_bf16 v[90:93], v[166:169], v[228:231], v[90:93]
	v_mfma_f32_16x16x32_bf16 v[82:85], v[178:181], v[228:231], v[82:85]
	v_mfma_f32_16x16x32_bf16 v[66:69], v[178:181], v[236:239], v[66:69]
	v_mfma_f32_16x16x32_bf16 v[74:77], v[166:169], v[236:239], v[74:77]
	s_setprio 0
	s_barrier
	s_add_i32 s22, s53, s26
	v_lshl_add_u64 v[140:141], v[140:141], 0, s[34:35]
	s_mov_b32 m0, s22
	ds_read_b128 v[190:193], v145 offset:49152
	ds_read_b128 v[194:197], v145 offset:50176
	ds_read_b128 v[198:201], v145 offset:51200
	ds_read_b128 v[202:205], v145 offset:52224
	ds_read_b128 v[206:209], v145 offset:53248
	ds_read_b128 v[228:231], v145 offset:54272
	ds_read_b128 v[232:235], v145 offset:55296
	ds_read_b128 v[236:239], v145 offset:56320
	global_load_lds_dwordx4 v[140:141], off
	s_add_i32 m0, s22, 0x2000
	s_add_u32 s18, s18, 0x100080
	v_lshl_add_u64 v[140:141], v[186:187], 0, s[34:35]
	s_addc_u32 s19, s19, 0
	s_add_i32 s22, s54, s26
	global_load_lds_dwordx4 v[140:141], off
	v_lshl_add_u64 v[140:141], s[18:19], 0, v[0:1]
	s_mov_b32 m0, s22
	s_nop 0
	global_load_lds_dwordx4 v[140:141], off
	v_lshl_add_u64 v[140:141], s[18:19], 0, v[130:131]
	s_add_i32 m0, s22, 0x2000
	s_nop 0
	global_load_lds_dwordx4 v[140:141], off
	v_lshl_add_u64 v[140:141], v[188:189], 0, s[34:35]
	s_mov_b32 m0, s43
	s_nop 0
	global_load_lds_dwordx4 v[140:141], off
	v_lshl_add_u64 v[140:141], v[210:211], 0, s[34:35]
	s_mov_b32 m0, s44
	s_nop 0
	global_load_lds_dwordx4 v[140:141], off
	s_waitcnt vmcnt(8)
	s_waitcnt lgkmcnt(0)
	s_barrier
	s_setprio 1
	s_waitcnt lgkmcnt(0)
	v_mfma_f32_16x16x32_bf16 v[62:65], v[146:149], v[190:193], v[62:65]
	v_mfma_f32_16x16x32_bf16 v[54:57], v[154:157], v[190:193], v[54:57]
	v_mfma_f32_16x16x32_bf16 v[38:41], v[154:157], v[198:201], v[38:41]
	v_mfma_f32_16x16x32_bf16 v[46:49], v[146:149], v[198:201], v[46:49]
	v_mfma_f32_16x16x32_bf16 v[30:33], v[146:149], v[206:209], v[30:33]
	v_mfma_f32_16x16x32_bf16 v[22:25], v[154:157], v[206:209], v[22:25]
	v_mfma_f32_16x16x32_bf16 v[6:9], v[154:157], v[232:235], v[6:9]
	v_mfma_f32_16x16x32_bf16 v[14:17], v[146:149], v[232:235], v[14:17]
	v_mfma_f32_16x16x32_bf16 v[62:65], v[150:153], v[194:197], v[62:65]
	v_mfma_f32_16x16x32_bf16 v[54:57], v[158:161], v[194:197], v[54:57]
	v_mfma_f32_16x16x32_bf16 v[38:41], v[158:161], v[202:205], v[38:41]
	v_mfma_f32_16x16x32_bf16 v[46:49], v[150:153], v[202:205], v[46:49]
	v_mfma_f32_16x16x32_bf16 v[30:33], v[150:153], v[228:231], v[30:33]
	v_mfma_f32_16x16x32_bf16 v[22:25], v[158:161], v[228:231], v[22:25]
	v_mfma_f32_16x16x32_bf16 v[6:9], v[158:161], v[236:239], v[6:9]
	v_mfma_f32_16x16x32_bf16 v[14:17], v[150:153], v[236:239], v[14:17]
	s_setprio 0
	s_setprio 1
	v_mfma_f32_16x16x32_bf16 v[58:61], v[162:165], v[190:193], v[58:61]
	v_mfma_f32_16x16x32_bf16 v[50:53], v[170:173], v[190:193], v[50:53]
	v_mfma_f32_16x16x32_bf16 v[34:37], v[170:173], v[198:201], v[34:37]
	v_mfma_f32_16x16x32_bf16 v[42:45], v[162:165], v[198:201], v[42:45]
	v_mfma_f32_16x16x32_bf16 v[26:29], v[162:165], v[206:209], v[26:29]
	v_mfma_f32_16x16x32_bf16 v[18:21], v[170:173], v[206:209], v[18:21]
	v_mfma_f32_16x16x32_bf16 v[2:5], v[170:173], v[232:235], v[2:5]
	v_mfma_f32_16x16x32_bf16 v[10:13], v[162:165], v[232:235], v[10:13]
	v_mfma_f32_16x16x32_bf16 v[58:61], v[166:169], v[194:197], v[58:61]
	v_mfma_f32_16x16x32_bf16 v[50:53], v[178:181], v[194:197], v[50:53]
	v_mfma_f32_16x16x32_bf16 v[34:37], v[178:181], v[202:205], v[34:37]
	v_mfma_f32_16x16x32_bf16 v[42:45], v[166:169], v[202:205], v[42:45]
	v_mfma_f32_16x16x32_bf16 v[26:29], v[166:169], v[228:231], v[26:29]
	v_mfma_f32_16x16x32_bf16 v[18:21], v[178:181], v[228:231], v[18:21]
	v_mfma_f32_16x16x32_bf16 v[2:5], v[178:181], v[236:239], v[2:5]
	v_mfma_f32_16x16x32_bf16 v[10:13], v[166:169], v[236:239], v[10:13]
	s_setprio 0
	s_barrier
	s_add_i32 s52, s52, 2
	s_add_u32 s16, s16, 0x100
	s_addc_u32 s17, s17, 0
	s_add_u32 s50, s50, 0x100
	s_addc_u32 s51, s51, 0
	s_cmp_gt_u32 s52, 61
	s_cbranch_scc0 .LBB0_721
	s_and_b64 vcc, exec, s[2:3]
	s_cbranch_vccz .LBB0_724
	s_barrier

.LBB0_805:
	s_add_u32 s16, s14, 0x100
	s_addc_u32 s17, s15, 0
	s_add_i32 s49, 0, 0x10000
	s_cmpk_eq_i32 s48, 0xa8
	s_cselect_b32 s23, s5, s17
	s_cselect_b32 s22, s4, s16
	v_add_u32_e32 v140, s49, v143
	s_cselect_b32 s19, s9, s47
	s_cselect_b32 s18, s8, s46
	s_add_i32 s50, 0, 0x14000
	ds_read_b128 v[146:149], v140
	ds_read_b128 v[150:153], v140 offset:1024
	ds_read_b128 v[154:157], v140 offset:2048
	ds_read_b128 v[158:161], v140 offset:3072
	v_add_u32_e32 v140, s50, v143
	ds_read_b128 v[162:165], v140
	ds_read_b128 v[166:169], v140 offset:1024
	ds_read_b128 v[170:173], v140 offset:2048
	ds_read_b128 v[178:181], v140 offset:3072
	v_lshl_add_u64 v[140:141], s[14:15], 0, v[136:137]
	s_add_i32 m0, s31, 0xc000
	ds_read_b128 v[190:193], v145
	ds_read_b128 v[194:197], v145 offset:1024
	ds_read_b128 v[198:201], v145 offset:2048
	ds_read_b128 v[202:205], v145 offset:3072
	ds_read_b128 v[206:209], v145 offset:4096
	ds_read_b128 v[228:231], v145 offset:5120
	ds_read_b128 v[232:235], v145 offset:6144
	ds_read_b128 v[236:239], v145 offset:7168
	global_load_lds_dwordx4 v[140:141], off
	v_lshl_add_u64 v[140:141], s[14:15], 0, v[138:139]
	s_add_i32 m0, s31, 0xe000
	s_nop 0
	global_load_lds_dwordx4 v[140:141], off
	s_waitcnt vmcnt(8)
	s_waitcnt lgkmcnt(0)
	s_barrier
	s_setprio 1
	s_waitcnt lgkmcnt(0)
	v_mfma_f32_16x16x32_bf16 v[126:129], v[146:149], v[190:193], v[126:129]
	v_mfma_f32_16x16x32_bf16 v[122:125], v[154:157], v[190:193], v[122:125]
	v_mfma_f32_16x16x32_bf16 v[110:113], v[154:157], v[198:201], v[110:113]
	v_mfma_f32_16x16x32_bf16 v[118:121], v[146:149], v[198:201], v[118:121]
	v_mfma_f32_16x16x32_bf16 v[102:105], v[146:149], v[206:209], v[102:105]
	v_mfma_f32_16x16x32_bf16 v[94:97], v[154:157], v[206:209], v[94:97]
	v_mfma_f32_16x16x32_bf16 v[78:81], v[154:157], v[232:235], v[78:81]
	v_mfma_f32_16x16x32_bf16 v[86:89], v[146:149], v[232:235], v[86:89]
	v_mfma_f32_16x16x32_bf16 v[126:129], v[150:153], v[194:197], v[126:129]
	v_mfma_f32_16x16x32_bf16 v[122:125], v[158:161], v[194:197], v[122:125]
	v_mfma_f32_16x16x32_bf16 v[110:113], v[158:161], v[202:205], v[110:113]
	v_mfma_f32_16x16x32_bf16 v[118:121], v[150:153], v[202:205], v[118:121]
	v_mfma_f32_16x16x32_bf16 v[102:105], v[150:153], v[228:231], v[102:105]
	v_mfma_f32_16x16x32_bf16 v[94:97], v[158:161], v[228:231], v[94:97]
	v_mfma_f32_16x16x32_bf16 v[78:81], v[158:161], v[236:239], v[78:81]
	v_mfma_f32_16x16x32_bf16 v[86:89], v[150:153], v[236:239], v[86:89]
	s_setprio 0
	s_setprio 1
	v_mfma_f32_16x16x32_bf16 v[114:117], v[162:165], v[190:193], v[114:117]
	v_mfma_f32_16x16x32_bf16 v[106:109], v[170:173], v[190:193], v[106:109]
	v_mfma_f32_16x16x32_bf16 v[90:93], v[170:173], v[198:201], v[90:93]
	v_mfma_f32_16x16x32_bf16 v[98:101], v[162:165], v[198:201], v[98:101]
	v_mfma_f32_16x16x32_bf16 v[82:85], v[162:165], v[206:209], v[82:85]
	v_mfma_f32_16x16x32_bf16 v[74:77], v[170:173], v[206:209], v[74:77]
	v_mfma_f32_16x16x32_bf16 v[66:69], v[170:173], v[232:235], v[66:69]
	v_mfma_f32_16x16x32_bf16 v[70:73], v[162:165], v[232:235], v[70:73]
	v_mfma_f32_16x16x32_bf16 v[114:117], v[166:169], v[194:197], v[114:117]
	v_mfma_f32_16x16x32_bf16 v[106:109], v[178:181], v[194:197], v[106:109]
	v_mfma_f32_16x16x32_bf16 v[90:93], v[178:181], v[202:205], v[90:93]
	v_mfma_f32_16x16x32_bf16 v[98:101], v[166:169], v[202:205], v[98:101]
	v_mfma_f32_16x16x32_bf16 v[82:85], v[166:169], v[228:231], v[82:85]
	v_mfma_f32_16x16x32_bf16 v[74:77], v[178:181], v[228:231], v[74:77]
	v_mfma_f32_16x16x32_bf16 v[66:69], v[178:181], v[236:239], v[66:69]
	v_mfma_f32_16x16x32_bf16 v[70:73], v[166:169], v[236:239], v[70:73]
	s_setprio 0
	s_barrier
	s_add_i32 s14, s49, s26
	v_lshl_add_u64 v[140:141], s[18:19], 0, v[0:1]
	s_mov_b32 m0, s14
	ds_read_b128 v[190:193], v145 offset:16384
	ds_read_b128 v[194:197], v145 offset:17408
	ds_read_b128 v[198:201], v145 offset:18432
	ds_read_b128 v[202:205], v145 offset:19456
	ds_read_b128 v[206:209], v145 offset:20480
	ds_read_b128 v[228:231], v145 offset:21504
	ds_read_b128 v[232:235], v145 offset:22528
	ds_read_b128 v[236:239], v145 offset:23552
	global_load_lds_dwordx4 v[140:141], off
	s_add_i32 m0, s14, 0x2000
	s_add_u32 s14, s18, 0x2b0000
	v_lshl_add_u64 v[186:187], s[18:19], 0, v[130:131]
	s_addc_u32 s15, s19, 0
	s_add_i32 s49, s50, s26
	global_load_lds_dwordx4 v[186:187], off
	v_lshl_add_u64 v[188:189], s[14:15], 0, v[0:1]
	s_mov_b32 m0, s49
	v_lshl_add_u64 v[210:211], s[22:23], 0, v[132:133]
	global_load_lds_dwordx4 v[188:189], off
	v_lshl_add_u64 v[188:189], s[14:15], 0, v[130:131]
	s_add_i32 m0, s49, 0x2000
	s_nop 0
	global_load_lds_dwordx4 v[188:189], off
	v_lshl_add_u64 v[188:189], s[22:23], 0, v[134:135]
	s_mov_b32 m0, s31
	s_nop 0
	global_load_lds_dwordx4 v[188:189], off
	s_mov_b32 m0, s36
	s_nop 0
	global_load_lds_dwordx4 v[210:211], off
	s_waitcnt vmcnt(8)
	s_waitcnt lgkmcnt(0)
	s_barrier
	s_setprio 1
	s_waitcnt lgkmcnt(0)
	v_mfma_f32_16x16x32_bf16 v[62:65], v[146:149], v[190:193], v[62:65]
	v_mfma_f32_16x16x32_bf16 v[58:61], v[154:157], v[190:193], v[58:61]
	v_mfma_f32_16x16x32_bf16 v[46:49], v[154:157], v[198:201], v[46:49]
	v_mfma_f32_16x16x32_bf16 v[54:57], v[146:149], v[198:201], v[54:57]
	v_mfma_f32_16x16x32_bf16 v[38:41], v[146:149], v[206:209], v[38:41]
	v_mfma_f32_16x16x32_bf16 v[30:33], v[154:157], v[206:209], v[30:33]
	v_mfma_f32_16x16x32_bf16 v[14:17], v[154:157], v[232:235], v[14:17]
	v_mfma_f32_16x16x32_bf16 v[22:25], v[146:149], v[232:235], v[22:25]
	v_mfma_f32_16x16x32_bf16 v[62:65], v[150:153], v[194:197], v[62:65]
	v_mfma_f32_16x16x32_bf16 v[58:61], v[158:161], v[194:197], v[58:61]
	v_mfma_f32_16x16x32_bf16 v[46:49], v[158:161], v[202:205], v[46:49]
	v_mfma_f32_16x16x32_bf16 v[54:57], v[150:153], v[202:205], v[54:57]
	v_mfma_f32_16x16x32_bf16 v[38:41], v[150:153], v[228:231], v[38:41]
	v_mfma_f32_16x16x32_bf16 v[30:33], v[158:161], v[228:231], v[30:33]
	v_mfma_f32_16x16x32_bf16 v[14:17], v[158:161], v[236:239], v[14:17]
	v_mfma_f32_16x16x32_bf16 v[22:25], v[150:153], v[236:239], v[22:25]
	s_setprio 0
	s_setprio 1
	v_mfma_f32_16x16x32_bf16 v[50:53], v[162:165], v[190:193], v[50:53]
	v_mfma_f32_16x16x32_bf16 v[42:45], v[170:173], v[190:193], v[42:45]
	v_mfma_f32_16x16x32_bf16 v[26:29], v[170:173], v[198:201], v[26:29]
	v_mfma_f32_16x16x32_bf16 v[34:37], v[162:165], v[198:201], v[34:37]
	v_mfma_f32_16x16x32_bf16 v[18:21], v[162:165], v[206:209], v[18:21]
	v_mfma_f32_16x16x32_bf16 v[10:13], v[170:173], v[206:209], v[10:13]
	v_mfma_f32_16x16x32_bf16 v[2:5], v[170:173], v[232:235], v[2:5]
	v_mfma_f32_16x16x32_bf16 v[6:9], v[162:165], v[232:235], v[6:9]
	v_mfma_f32_16x16x32_bf16 v[50:53], v[166:169], v[194:197], v[50:53]
	v_mfma_f32_16x16x32_bf16 v[42:45], v[178:181], v[194:197], v[42:45]
	v_mfma_f32_16x16x32_bf16 v[26:29], v[178:181], v[202:205], v[26:29]
	v_mfma_f32_16x16x32_bf16 v[34:37], v[166:169], v[202:205], v[34:37]
	v_mfma_f32_16x16x32_bf16 v[18:21], v[166:169], v[228:231], v[18:21]
	v_mfma_f32_16x16x32_bf16 v[10:13], v[178:181], v[228:231], v[10:13]
	v_mfma_f32_16x16x32_bf16 v[2:5], v[178:181], v[236:239], v[2:5]
	v_mfma_f32_16x16x32_bf16 v[6:9], v[166:169], v[236:239], v[6:9]
	s_setprio 0
	s_barrier
	s_add_i32 s49, 0, 0x18000
	s_add_i32 s50, 0, 0x1c000
	v_add_u32_e32 v158, s49, v143
	v_add_u32_e32 v175, s50, v143
	ds_read_b128 v[146:149], v158
	ds_read_b128 v[150:153], v158 offset:1024
	ds_read_b128 v[154:157], v158 offset:2048
	ds_read_b128 v[158:161], v158 offset:3072
	ds_read_b128 v[162:165], v175
	ds_read_b128 v[166:169], v175 offset:1024
	ds_read_b128 v[170:173], v175 offset:2048
	ds_read_b128 v[178:181], v175 offset:3072
	s_add_u32 s14, s22, 0x2b0000
	s_addc_u32 s15, s23, 0
	s_mov_b32 m0, s37
	v_lshl_add_u64 v[226:227], s[14:15], 0, v[134:135]
	ds_read_b128 v[190:193], v145 offset:32768
	ds_read_b128 v[194:197], v145 offset:33792
	ds_read_b128 v[198:201], v145 offset:34816
	ds_read_b128 v[202:205], v145 offset:35840
	ds_read_b128 v[206:209], v145 offset:36864
	ds_read_b128 v[228:231], v145 offset:37888
	ds_read_b128 v[232:235], v145 offset:38912
	ds_read_b128 v[236:239], v145 offset:39936
	global_load_lds_dwordx4 v[226:227], off
	v_lshl_add_u64 v[226:227], s[14:15], 0, v[132:133]
	s_mov_b32 m0, s38
	s_nop 0
	global_load_lds_dwordx4 v[226:227], off
	s_waitcnt vmcnt(8)
	s_waitcnt lgkmcnt(0)
	s_barrier
	s_setprio 1
	s_waitcnt lgkmcnt(0)
	v_mfma_f32_16x16x32_bf16 v[126:129], v[146:149], v[190:193], v[126:129]
	v_mfma_f32_16x16x32_bf16 v[122:125], v[154:157], v[190:193], v[122:125]
	v_mfma_f32_16x16x32_bf16 v[110:113], v[154:157], v[198:201], v[110:113]
	v_mfma_f32_16x16x32_bf16 v[118:121], v[146:149], v[198:201], v[118:121]
	v_mfma_f32_16x16x32_bf16 v[102:105], v[146:149], v[206:209], v[102:105]
	v_mfma_f32_16x16x32_bf16 v[94:97], v[154:157], v[206:209], v[94:97]
	v_mfma_f32_16x16x32_bf16 v[78:81], v[154:157], v[232:235], v[78:81]
	v_mfma_f32_16x16x32_bf16 v[86:89], v[146:149], v[232:235], v[86:89]
	v_mfma_f32_16x16x32_bf16 v[126:129], v[150:153], v[194:197], v[126:129]
	v_mfma_f32_16x16x32_bf16 v[122:125], v[158:161], v[194:197], v[122:125]
	v_mfma_f32_16x16x32_bf16 v[110:113], v[158:161], v[202:205], v[110:113]
	v_mfma_f32_16x16x32_bf16 v[118:121], v[150:153], v[202:205], v[118:121]
	v_mfma_f32_16x16x32_bf16 v[102:105], v[150:153], v[228:231], v[102:105]
	v_mfma_f32_16x16x32_bf16 v[94:97], v[158:161], v[228:231], v[94:97]
	v_mfma_f32_16x16x32_bf16 v[78:81], v[158:161], v[236:239], v[78:81]
	v_mfma_f32_16x16x32_bf16 v[86:89], v[150:153], v[236:239], v[86:89]
	s_setprio 0
	s_setprio 1
	v_mfma_f32_16x16x32_bf16 v[114:117], v[162:165], v[190:193], v[114:117]
	v_mfma_f32_16x16x32_bf16 v[106:109], v[170:173], v[190:193], v[106:109]
	v_mfma_f32_16x16x32_bf16 v[90:93], v[170:173], v[198:201], v[90:93]
	v_mfma_f32_16x16x32_bf16 v[98:101], v[162:165], v[198:201], v[98:101]
	v_mfma_f32_16x16x32_bf16 v[82:85], v[162:165], v[206:209], v[82:85]
	v_mfma_f32_16x16x32_bf16 v[74:77], v[170:173], v[206:209], v[74:77]
	v_mfma_f32_16x16x32_bf16 v[66:69], v[170:173], v[232:235], v[66:69]
	v_mfma_f32_16x16x32_bf16 v[70:73], v[162:165], v[232:235], v[70:73]
	v_mfma_f32_16x16x32_bf16 v[114:117], v[166:169], v[194:197], v[114:117]
	v_mfma_f32_16x16x32_bf16 v[106:109], v[178:181], v[194:197], v[106:109]
	v_mfma_f32_16x16x32_bf16 v[90:93], v[178:181], v[202:205], v[90:93]
	v_mfma_f32_16x16x32_bf16 v[98:101], v[166:169], v[202:205], v[98:101]
	v_mfma_f32_16x16x32_bf16 v[82:85], v[166:169], v[228:231], v[82:85]
	v_mfma_f32_16x16x32_bf16 v[74:77], v[178:181], v[228:231], v[74:77]
	v_mfma_f32_16x16x32_bf16 v[66:69], v[178:181], v[236:239], v[66:69]
	v_mfma_f32_16x16x32_bf16 v[70:73], v[166:169], v[236:239], v[70:73]
	s_setprio 0
	s_barrier
	s_add_i32 s14, s49, s26
	v_lshl_add_u64 v[140:141], v[140:141], 0, s[34:35]
	s_mov_b32 m0, s14
	ds_read_b128 v[190:193], v145 offset:49152
	ds_read_b128 v[194:197], v145 offset:50176
	ds_read_b128 v[198:201], v145 offset:51200
	ds_read_b128 v[202:205], v145 offset:52224
	ds_read_b128 v[206:209], v145 offset:53248
	ds_read_b128 v[228:231], v145 offset:54272
	ds_read_b128 v[232:235], v145 offset:55296
	ds_read_b128 v[236:239], v145 offset:56320
	global_load_lds_dwordx4 v[140:141], off
	s_add_i32 m0, s14, 0x2000
	s_add_u32 s14, s18, 0x2b0080
	v_lshl_add_u64 v[140:141], v[186:187], 0, s[34:35]
	s_addc_u32 s15, s19, 0
	s_add_i32 s18, s50, s26
	global_load_lds_dwordx4 v[140:141], off
	v_lshl_add_u64 v[140:141], s[14:15], 0, v[0:1]
	s_mov_b32 m0, s18
	s_nop 0
	global_load_lds_dwordx4 v[140:141], off
	v_lshl_add_u64 v[140:141], s[14:15], 0, v[130:131]
	s_add_i32 m0, s18, 0x2000
	s_nop 0
	global_load_lds_dwordx4 v[140:141], off
	v_lshl_add_u64 v[140:141], v[188:189], 0, s[34:35]
	s_mov_b32 m0, s39
	s_nop 0
	global_load_lds_dwordx4 v[140:141], off
	v_lshl_add_u64 v[140:141], v[210:211], 0, s[34:35]
	s_mov_b32 m0, s40
	s_nop 0
	global_load_lds_dwordx4 v[140:141], off
	s_waitcnt vmcnt(8)
	s_waitcnt lgkmcnt(0)
	s_barrier
	s_setprio 1
	s_waitcnt lgkmcnt(0)
	v_mfma_f32_16x16x32_bf16 v[62:65], v[146:149], v[190:193], v[62:65]
	v_mfma_f32_16x16x32_bf16 v[58:61], v[154:157], v[190:193], v[58:61]
	v_mfma_f32_16x16x32_bf16 v[46:49], v[154:157], v[198:201], v[46:49]
	v_mfma_f32_16x16x32_bf16 v[54:57], v[146:149], v[198:201], v[54:57]
	v_mfma_f32_16x16x32_bf16 v[38:41], v[146:149], v[206:209], v[38:41]
	v_mfma_f32_16x16x32_bf16 v[30:33], v[154:157], v[206:209], v[30:33]
	v_mfma_f32_16x16x32_bf16 v[14:17], v[154:157], v[232:235], v[14:17]
	v_mfma_f32_16x16x32_bf16 v[22:25], v[146:149], v[232:235], v[22:25]
	v_mfma_f32_16x16x32_bf16 v[62:65], v[150:153], v[194:197], v[62:65]
	v_mfma_f32_16x16x32_bf16 v[58:61], v[158:161], v[194:197], v[58:61]
	v_mfma_f32_16x16x32_bf16 v[46:49], v[158:161], v[202:205], v[46:49]
	v_mfma_f32_16x16x32_bf16 v[54:57], v[150:153], v[202:205], v[54:57]
	v_mfma_f32_16x16x32_bf16 v[38:41], v[150:153], v[228:231], v[38:41]
	v_mfma_f32_16x16x32_bf16 v[30:33], v[158:161], v[228:231], v[30:33]
	v_mfma_f32_16x16x32_bf16 v[14:17], v[158:161], v[236:239], v[14:17]
	v_mfma_f32_16x16x32_bf16 v[22:25], v[150:153], v[236:239], v[22:25]
	s_setprio 0
	s_setprio 1
	v_mfma_f32_16x16x32_bf16 v[50:53], v[162:165], v[190:193], v[50:53]
	v_mfma_f32_16x16x32_bf16 v[42:45], v[170:173], v[190:193], v[42:45]
	v_mfma_f32_16x16x32_bf16 v[26:29], v[170:173], v[198:201], v[26:29]
	v_mfma_f32_16x16x32_bf16 v[34:37], v[162:165], v[198:201], v[34:37]
	v_mfma_f32_16x16x32_bf16 v[18:21], v[162:165], v[206:209], v[18:21]
	v_mfma_f32_16x16x32_bf16 v[10:13], v[170:173], v[206:209], v[10:13]
	v_mfma_f32_16x16x32_bf16 v[2:5], v[170:173], v[232:235], v[2:5]
	v_mfma_f32_16x16x32_bf16 v[6:9], v[162:165], v[232:235], v[6:9]
	v_mfma_f32_16x16x32_bf16 v[50:53], v[166:169], v[194:197], v[50:53]
	v_mfma_f32_16x16x32_bf16 v[42:45], v[178:181], v[194:197], v[42:45]
	v_mfma_f32_16x16x32_bf16 v[26:29], v[178:181], v[202:205], v[26:29]
	v_mfma_f32_16x16x32_bf16 v[34:37], v[166:169], v[202:205], v[34:37]
	v_mfma_f32_16x16x32_bf16 v[18:21], v[166:169], v[228:231], v[18:21]
	v_mfma_f32_16x16x32_bf16 v[10:13], v[178:181], v[228:231], v[10:13]
	v_mfma_f32_16x16x32_bf16 v[2:5], v[178:181], v[236:239], v[2:5]
	v_mfma_f32_16x16x32_bf16 v[6:9], v[166:169], v[236:239], v[6:9]
	s_setprio 0
	s_barrier
	s_add_i32 s48, s48, 2
	s_add_u32 s46, s46, 0x100
	s_addc_u32 s47, s47, 0
	s_cmpk_gt_u32 s48, 0xa9
	s_mov_b64 s[14:15], s[16:17]
	s_cbranch_scc0 .LBB0_805
	s_and_b64 vcc, exec, s[6:7]
	s_cbranch_vccz .LBB0_808
	s_barrier
